# merge phase: gate-ratio hook loads overlapped pairwise; merge_final gate loads prefetched up front
# speedup vs baseline: 1.0189x; 1.0189x over previous
; DI void st8(bf16_t* dst, const float (&v)[8]) { u32x4 o = {pk2(v[0], v[1]), pk2(v[2], v[3]), pk2(v[4], v[5]), pk2(v[6], v[7])}; *(u32x4*)dst = o; }
; DI float dq8(unsigned w, int k) { return (float)((w >> (8 * k)) & 255u) * (1.f / 255.f); }
; DI u32x4* gate_slot(const Params& P, int tile, int j, int g8) { return (u32x4*)slotp(P, SL_SK) + ((size_t)(tile * 3 + j) * 8 + g8) * 512 + tid(); }
; DI void merge_final(const Params& P, int tile, bf16_t* __restrict__ hb, const f32x4 (&acc)[2][2][4][2], int m0, int n0) {
;     LANE_DECODE; (void)lane;
; #pragma unroll
;     for (int ai = 0; ai < 2; ++ai)
; #pragma unroll
;         for (int bj = 0; bj < 2; ++bj)
; #pragma unroll
;             for (int nn = 0; nn < 2; ++nn) {
;                 const size_t tok = (size_t)m0 + bj * 128 + wc * 32 + nn * 16 + fr;
;                 const int col = n0 + ai * 128 + wr * 64 + 8 * fq;
;                 float lo[8], hi[8];
;                 grp16(acc, ai, bj, nn, 1.f, lo, hi);
;                 const u32x4 gq = *gate_slot(P, tile, 2, ai * 4 + bj * 2 + nn);
; #pragma unroll
;                 for (int e = 0; e < 8; ++e) { lo[e] *= dq8(gq[e >> 2], e & 3); hi[e] *= dq8(gq[2 + (e >> 2)], e & 3); }
;                 bf16_t* hp = hb + tok * 1024 + col;
;                 st8(hp, lo); st8(hp + 32, hi);
;                 __builtin_amdgcn_sched_barrier(0);
;             }
; }
.LBB0_42:
	s_or_b64 exec, exec, s[20:21]
	v_mov_b32_e32 v0, v162
	v_mov_b32_e32 v134, v162
	v_readlane_b32 s2, v255, 32
	v_ashrrev_i32_e32 v135, 31, v134
	v_lshl_add_u64 v[134:135], v[134:135], 4, s[8:9]
	s_mov_b64 s[0:1], 0x2000
	v_mov_b64_e32 v[216:217], v[134:135]
	global_load_dwordx4 v[184:187], v[216:217], off
	v_lshl_add_u64 v[216:217], v[216:217], 0, s[0:1]
	global_load_dwordx4 v[188:191], v[216:217], off
	v_lshl_add_u64 v[216:217], v[216:217], 0, s[0:1]
	global_load_dwordx4 v[192:195], v[216:217], off
	v_lshl_add_u64 v[216:217], v[216:217], 0, s[0:1]
	global_load_dwordx4 v[196:199], v[216:217], off
	v_lshl_add_u64 v[216:217], v[216:217], 0, s[0:1]
	global_load_dwordx4 v[200:203], v[216:217], off
	v_lshl_add_u64 v[216:217], v[216:217], 0, s[0:1]
	global_load_dwordx4 v[204:207], v[216:217], off
	v_lshl_add_u64 v[216:217], v[216:217], 0, s[0:1]
	global_load_dwordx4 v[208:211], v[216:217], off
	v_lshl_add_u64 v[216:217], v[216:217], 0, s[0:1]
	global_load_dwordx4 v[212:215], v[216:217], off
	v_and_b32_e32 v130, 15, v0
	v_lshrrev_b32_e32 v131, 1, v0
	v_ashrrev_i32_e32 v0, 2, v0
	v_and_b32_e32 v0, 0xffffffc0, v0
	v_and_b32_e32 v132, 0x60, v131
	v_add_u32_e32 v0, s14, v0
	v_or3_b32 v140, v130, v132, s49
	v_and_or_b32 v130, v131, 24, v0
	v_ashrrev_i32_e32 v131, 31, v130
	v_readlane_b32 s3, v255, 33
	v_lshlrev_b32_e32 v0, 11, v140
	s_waitcnt vmcnt(7)
	s_nop 1
	v_mov_b64_e32 v[136:137], v[184:185]
	v_mov_b64_e32 v[138:139], v[186:187]
	v_cvt_f32_ubyte1_e32 v135, v136
	v_cvt_f32_ubyte0_e32 v134, v136
	v_pk_mul_f32 v[134:135], v[134:135], s[84:85] op_sel_hi:[1,0]
	v_lshl_add_u64 v[132:133], v[130:131], 1, s[2:3]
	v_pk_mul_f32 v[134:135], v[122:123], v[134:135]
	v_cvt_f32_ubyte1_e32 v123, v138
	v_cvt_f32_ubyte0_e32 v122, v138
	v_pk_mul_f32 v[122:123], v[122:123], s[84:85] op_sel_hi:[1,0]
	v_cvt_pk_bf16_f32 v134, v134, v135
	v_pk_mul_f32 v[122:123], v[126:127], v[122:123]
	v_cvt_f32_ubyte3_e32 v127, v136
	v_cvt_f32_ubyte2_e32 v126, v136
	v_pk_mul_f32 v[126:127], v[126:127], s[84:85] op_sel_hi:[1,0]
	s_nop 0
	v_pk_mul_f32 v[126:127], v[124:125], v[126:127]
	v_cvt_f32_ubyte3_e32 v125, v138
	v_cvt_f32_ubyte2_e32 v124, v138
	v_pk_mul_f32 v[124:125], v[124:125], s[84:85] op_sel_hi:[1,0]
	v_cvt_pk_bf16_f32 v135, v126, v127
	v_pk_mul_f32 v[124:125], v[128:129], v[124:125]
	v_cvt_f32_ubyte1_e32 v129, v137
	v_cvt_f32_ubyte0_e32 v128, v137
	v_pk_mul_f32 v[128:129], v[128:129], s[84:85] op_sel_hi:[1,0]
	s_nop 0
	v_pk_mul_f32 v[128:129], v[114:115], v[128:129]
	v_cvt_f32_ubyte1_e32 v115, v139
	v_cvt_f32_ubyte0_e32 v114, v139
	v_pk_mul_f32 v[114:115], v[114:115], s[84:85] op_sel_hi:[1,0]
	v_cvt_pk_bf16_f32 v136, v128, v129
	v_pk_mul_f32 v[114:115], v[118:119], v[114:115]
	v_cvt_f32_ubyte3_e32 v119, v137
	v_cvt_f32_ubyte2_e32 v118, v137
	v_pk_mul_f32 v[118:119], v[118:119], s[84:85] op_sel_hi:[1,0]
	s_nop 0
	v_pk_mul_f32 v[118:119], v[116:117], v[118:119]
	v_cvt_f32_ubyte3_e32 v117, v139
	v_cvt_f32_ubyte2_e32 v116, v139
	v_pk_mul_f32 v[116:117], v[116:117], s[84:85] op_sel_hi:[1,0]
	v_lshl_add_u64 v[138:139], v[132:133], 0, v[0:1]
	v_pk_mul_f32 v[116:117], v[120:121], v[116:117]
	v_cvt_pk_bf16_f32 v137, v118, v119
	v_cvt_pk_bf16_f32 v118, v122, v123
	v_cvt_pk_bf16_f32 v119, v124, v125
	v_cvt_pk_bf16_f32 v120, v114, v115
	v_cvt_pk_bf16_f32 v121, v116, v117
	global_store_dwordx4 v[138:139], v[134:137], off
	global_store_dwordx4 v[138:139], v[118:121], off offset:64
	v_mov_b32_e32 v114, v162
	s_nop 0
	v_ashrrev_i32_e32 v115, 31, v114
	v_lshl_add_u64 v[114:115], v[114:115], 4, s[58:59]
	s_waitcnt vmcnt(8)
	s_nop 1
	v_mov_b64_e32 v[116:117], v[188:189]
	v_mov_b64_e32 v[118:119], v[190:191]
	v_cvt_f32_ubyte1_e32 v115, v116
	v_cvt_f32_ubyte0_e32 v114, v116
	v_pk_mul_f32 v[114:115], v[114:115], s[84:85] op_sel_hi:[1,0]
	s_nop 0
	v_pk_mul_f32 v[114:115], v[106:107], v[114:115]
	v_cvt_f32_ubyte1_e32 v107, v118
	v_cvt_f32_ubyte0_e32 v106, v118
	v_pk_mul_f32 v[106:107], v[106:107], s[84:85] op_sel_hi:[1,0]
	s_nop 0
	v_pk_mul_f32 v[106:107], v[110:111], v[106:107]
	v_cvt_f32_ubyte3_e32 v111, v116
	v_cvt_f32_ubyte2_e32 v110, v116
	v_pk_mul_f32 v[110:111], v[110:111], s[84:85] op_sel_hi:[1,0]
	s_nop 0
	v_pk_mul_f32 v[110:111], v[108:109], v[110:111]
	v_cvt_f32_ubyte3_e32 v109, v118
	v_cvt_f32_ubyte2_e32 v108, v118
	v_pk_mul_f32 v[108:109], v[108:109], s[84:85] op_sel_hi:[1,0]
	v_cvt_pk_bf16_f32 v118, v114, v115
	v_pk_mul_f32 v[108:109], v[112:113], v[108:109]
	v_cvt_f32_ubyte1_e32 v113, v117
	v_cvt_f32_ubyte0_e32 v112, v117
	v_pk_mul_f32 v[112:113], v[112:113], s[84:85] op_sel_hi:[1,0]
	s_nop 0
	v_pk_mul_f32 v[112:113], v[98:99], v[112:113]
	v_cvt_f32_ubyte1_e32 v99, v119
	v_cvt_f32_ubyte0_e32 v98, v119
	v_pk_mul_f32 v[98:99], v[98:99], s[84:85] op_sel_hi:[1,0]
	v_cvt_pk_bf16_f32 v120, v112, v113
	v_pk_mul_f32 v[102:103], v[102:103], v[98:99]
	v_cvt_f32_ubyte3_e32 v99, v117
	v_cvt_f32_ubyte2_e32 v98, v117
	v_pk_mul_f32 v[98:99], v[98:99], s[84:85] op_sel_hi:[1,0]
	s_nop 0
	v_pk_mul_f32 v[116:117], v[100:101], v[98:99]
	v_cvt_f32_ubyte3_e32 v99, v119
	v_cvt_f32_ubyte2_e32 v98, v119
	v_pk_mul_f32 v[98:99], v[98:99], s[84:85] op_sel_hi:[1,0]
	v_cvt_pk_bf16_f32 v119, v110, v111
	v_pk_mul_f32 v[100:101], v[104:105], v[98:99]
	v_or_b32_e32 v98, 0x8000, v0
	v_mov_b32_e32 v99, v1
	v_lshl_add_u64 v[122:123], v[132:133], 0, v[98:99]
	v_cvt_pk_bf16_f32 v121, v116, v117
	v_cvt_pk_bf16_f32 v104, v106, v107
	v_cvt_pk_bf16_f32 v105, v108, v109
	v_cvt_pk_bf16_f32 v106, v102, v103
	v_cvt_pk_bf16_f32 v107, v100, v101
	global_store_dwordx4 v[122:123], v[118:121], off
	global_store_dwordx4 v[122:123], v[104:107], off offset:64
	v_mov_b32_e32 v100, v162
	s_nop 0
	v_ashrrev_i32_e32 v101, 31, v100
	v_lshl_add_u64 v[100:101], v[100:101], 4, s[56:57]
	s_waitcnt vmcnt(9)
; DI void st8(bf16_t* dst, const float (&v)[8]) { u32x4 o = {pk2(v[0], v[1]), pk2(v[2], v[3]), pk2(v[4], v[5]), pk2(v[6], v[7])}; *(u32x4*)dst = o; }
; DI float dq8(unsigned w, int k) { return (float)((w >> (8 * k)) & 255u) * (1.f / 255.f); }
; DI u32x4* gate_slot(const Params& P, int tile, int j, int g8) { return (u32x4*)slotp(P, SL_SK) + ((size_t)(tile * 3 + j) * 8 + g8) * 512 + tid(); }
; DI void merge_final(const Params& P, int tile, bf16_t* __restrict__ hb, const f32x4 (&acc)[2][2][4][2], int m0, int n0) {
;     ...
;             for (int nn = 0; nn < 2; ++nn) {
;                 const size_t tok = (size_t)m0 + bj * 128 + wc * 32 + nn * 16 + fr;
;                 const int col = n0 + ai * 128 + wr * 64 + 8 * fq;
;                 float lo[8], hi[8];
;                 grp16(acc, ai, bj, nn, 1.f, lo, hi);
;                 const u32x4 gq = *gate_slot(P, tile, 2, ai * 4 + bj * 2 + nn);
; #pragma unroll
;                 for (int e = 0; e < 8; ++e) { lo[e] *= dq8(gq[e >> 2], e & 3); hi[e] *= dq8(gq[2 + (e >> 2)], e & 3); }
;                 bf16_t* hp = hb + tok * 1024 + col;
;                 st8(hp, lo); st8(hp + 32, hi);
;                 __builtin_amdgcn_sched_barrier(0);
;             }
	s_nop 1
	v_mov_b64_e32 v[102:103], v[192:193]
	v_mov_b64_e32 v[104:105], v[194:195]
	v_cvt_f32_ubyte1_e32 v101, v102
	v_cvt_f32_ubyte0_e32 v100, v102
	v_pk_mul_f32 v[100:101], v[100:101], s[84:85] op_sel_hi:[1,0]
	s_nop 0
	v_pk_mul_f32 v[100:101], v[90:91], v[100:101]
	v_cvt_f32_ubyte1_e32 v91, v104
	v_cvt_f32_ubyte0_e32 v90, v104
	v_pk_mul_f32 v[90:91], v[90:91], s[84:85] op_sel_hi:[1,0]
	s_nop 0
	v_pk_mul_f32 v[90:91], v[94:95], v[90:91]
	v_cvt_f32_ubyte3_e32 v95, v102
	v_cvt_f32_ubyte2_e32 v94, v102
	v_pk_mul_f32 v[94:95], v[94:95], s[84:85] op_sel_hi:[1,0]
	s_nop 0
	v_pk_mul_f32 v[94:95], v[92:93], v[94:95]
	v_cvt_f32_ubyte3_e32 v93, v104
	v_cvt_f32_ubyte2_e32 v92, v104
	v_pk_mul_f32 v[92:93], v[92:93], s[84:85] op_sel_hi:[1,0]
	v_cvt_pk_bf16_f32 v104, v100, v101
	v_pk_mul_f32 v[92:93], v[96:97], v[92:93]
	v_cvt_f32_ubyte1_e32 v97, v103
	v_cvt_f32_ubyte0_e32 v96, v103
	v_pk_mul_f32 v[96:97], v[96:97], s[84:85] op_sel_hi:[1,0]
	s_nop 0
	v_pk_mul_f32 v[96:97], v[82:83], v[96:97]
	v_cvt_f32_ubyte1_e32 v83, v105
	v_cvt_f32_ubyte0_e32 v82, v105
	v_pk_mul_f32 v[82:83], v[82:83], s[84:85] op_sel_hi:[1,0]
	v_cvt_pk_bf16_f32 v106, v96, v97
	v_pk_mul_f32 v[86:87], v[86:87], v[82:83]
	v_cvt_f32_ubyte3_e32 v83, v103
	v_cvt_f32_ubyte2_e32 v82, v103
	v_pk_mul_f32 v[82:83], v[82:83], s[84:85] op_sel_hi:[1,0]
	s_nop 0
	v_pk_mul_f32 v[102:103], v[84:85], v[82:83]
	v_cvt_f32_ubyte3_e32 v83, v105
	v_cvt_f32_ubyte2_e32 v82, v105
	v_pk_mul_f32 v[82:83], v[82:83], s[84:85] op_sel_hi:[1,0]
	v_cvt_pk_bf16_f32 v105, v94, v95
	v_pk_mul_f32 v[84:85], v[88:89], v[82:83]
	v_or_b32_e32 v82, 0x40000, v0
	v_mov_b32_e32 v83, v1
	v_lshl_add_u64 v[108:109], v[132:133], 0, v[82:83]
	v_cvt_pk_bf16_f32 v107, v102, v103
	v_cvt_pk_bf16_f32 v88, v90, v91
	v_cvt_pk_bf16_f32 v89, v92, v93
	v_cvt_pk_bf16_f32 v90, v86, v87
	v_cvt_pk_bf16_f32 v91, v84, v85
	global_store_dwordx4 v[108:109], v[104:107], off
	global_store_dwordx4 v[108:109], v[88:91], off offset:64
	v_mov_b32_e32 v84, v162
	s_nop 0
	v_ashrrev_i32_e32 v85, 31, v84
	v_lshl_add_u64 v[84:85], v[84:85], 4, s[54:55]
	s_waitcnt vmcnt(10)
	s_nop 1
	v_mov_b64_e32 v[86:87], v[196:197]
	v_mov_b64_e32 v[88:89], v[198:199]
	v_cvt_f32_ubyte1_e32 v85, v86
	v_cvt_f32_ubyte0_e32 v84, v86
	v_pk_mul_f32 v[84:85], v[84:85], s[84:85] op_sel_hi:[1,0]
	s_nop 0
	v_pk_mul_f32 v[84:85], v[74:75], v[84:85]
	v_cvt_f32_ubyte1_e32 v75, v88
	v_cvt_f32_ubyte0_e32 v74, v88
	v_pk_mul_f32 v[74:75], v[74:75], s[84:85] op_sel_hi:[1,0]
	s_nop 0
	v_pk_mul_f32 v[74:75], v[78:79], v[74:75]
	v_cvt_f32_ubyte3_e32 v79, v86
	v_cvt_f32_ubyte2_e32 v78, v86
	v_pk_mul_f32 v[78:79], v[78:79], s[84:85] op_sel_hi:[1,0]
	s_nop 0
	v_pk_mul_f32 v[78:79], v[76:77], v[78:79]
	v_cvt_f32_ubyte3_e32 v77, v88
	v_cvt_f32_ubyte2_e32 v76, v88
	v_pk_mul_f32 v[76:77], v[76:77], s[84:85] op_sel_hi:[1,0]
	v_cvt_pk_bf16_f32 v88, v84, v85
	v_pk_mul_f32 v[76:77], v[80:81], v[76:77]
	v_cvt_f32_ubyte1_e32 v81, v87
	v_cvt_f32_ubyte0_e32 v80, v87
	v_pk_mul_f32 v[80:81], v[80:81], s[84:85] op_sel_hi:[1,0]
	s_nop 0
	v_pk_mul_f32 v[80:81], v[66:67], v[80:81]
	v_cvt_f32_ubyte1_e32 v67, v89
	v_cvt_f32_ubyte0_e32 v66, v89
	v_pk_mul_f32 v[66:67], v[66:67], s[84:85] op_sel_hi:[1,0]
	v_cvt_pk_bf16_f32 v90, v80, v81
	v_pk_mul_f32 v[70:71], v[70:71], v[66:67]
	v_cvt_f32_ubyte3_e32 v67, v87
	v_cvt_f32_ubyte2_e32 v66, v87
	v_pk_mul_f32 v[66:67], v[66:67], s[84:85] op_sel_hi:[1,0]
	s_nop 0
	v_pk_mul_f32 v[86:87], v[68:69], v[66:67]
	v_cvt_f32_ubyte3_e32 v67, v89
	v_cvt_f32_ubyte2_e32 v66, v89
	v_pk_mul_f32 v[66:67], v[66:67], s[84:85] op_sel_hi:[1,0]
	v_cvt_pk_bf16_f32 v89, v78, v79
	v_pk_mul_f32 v[68:69], v[72:73], v[66:67]
	v_or_b32_e32 v66, 0x48000, v0
	v_mov_b32_e32 v67, v1
	v_lshl_add_u64 v[92:93], v[132:133], 0, v[66:67]
	v_cvt_pk_bf16_f32 v91, v86, v87
	v_cvt_pk_bf16_f32 v72, v74, v75
	v_cvt_pk_bf16_f32 v73, v76, v77
	v_cvt_pk_bf16_f32 v74, v70, v71
	v_cvt_pk_bf16_f32 v75, v68, v69
	global_store_dwordx4 v[92:93], v[88:91], off
	global_store_dwordx4 v[92:93], v[72:75], off offset:64
	v_mov_b32_e32 v70, v162
	v_add_u32_e32 v68, 0x80, v130
	v_ashrrev_i32_e32 v71, 31, v70
	v_lshl_add_u64 v[70:71], v[70:71], 4, s[6:7]
	v_ashrrev_i32_e32 v69, 31, v68
	v_lshl_add_u64 v[68:69], v[68:69], 1, s[2:3]
	s_waitcnt vmcnt(11)
	s_nop 1
	v_mov_b64_e32 v[72:73], v[200:201]
	v_mov_b64_e32 v[74:75], v[202:203]
	v_cvt_f32_ubyte1_e32 v71, v72
	v_cvt_f32_ubyte0_e32 v70, v72
	v_pk_mul_f32 v[70:71], v[70:71], s[84:85] op_sel_hi:[1,0]
	s_nop 0
	v_pk_mul_f32 v[70:71], v[58:59], v[70:71]
	v_cvt_f32_ubyte1_e32 v59, v74
	v_cvt_f32_ubyte0_e32 v58, v74
	v_pk_mul_f32 v[58:59], v[58:59], s[84:85] op_sel_hi:[1,0]
	v_cvt_pk_bf16_f32 v70, v70, v71
	v_pk_mul_f32 v[58:59], v[62:63], v[58:59]
	v_cvt_f32_ubyte3_e32 v63, v72
	v_cvt_f32_ubyte2_e32 v62, v72
	v_pk_mul_f32 v[62:63], v[62:63], s[84:85] op_sel_hi:[1,0]
	s_nop 0
	v_pk_mul_f32 v[62:63], v[60:61], v[62:63]
	v_cvt_f32_ubyte3_e32 v61, v74
	v_cvt_f32_ubyte2_e32 v60, v74
	v_pk_mul_f32 v[60:61], v[60:61], s[84:85] op_sel_hi:[1,0]
	v_cvt_pk_bf16_f32 v71, v62, v63
	v_pk_mul_f32 v[60:61], v[64:65], v[60:61]
	v_cvt_f32_ubyte1_e32 v65, v73
	v_cvt_f32_ubyte0_e32 v64, v73
	v_pk_mul_f32 v[64:65], v[64:65], s[84:85] op_sel_hi:[1,0]
	s_nop 0
	v_pk_mul_f32 v[64:65], v[50:51], v[64:65]
	v_cvt_f32_ubyte1_e32 v51, v75
	v_cvt_f32_ubyte0_e32 v50, v75
	v_pk_mul_f32 v[50:51], v[50:51], s[84:85] op_sel_hi:[1,0]
	v_cvt_pk_bf16_f32 v72, v64, v65
	v_pk_mul_f32 v[50:51], v[54:55], v[50:51]
	v_cvt_f32_ubyte3_e32 v55, v73
	v_cvt_f32_ubyte2_e32 v54, v73
	v_pk_mul_f32 v[54:55], v[54:55], s[84:85] op_sel_hi:[1,0]
	s_nop 0
	v_pk_mul_f32 v[54:55], v[52:53], v[54:55]
	v_cvt_f32_ubyte3_e32 v53, v75
	v_cvt_f32_ubyte2_e32 v52, v75
	v_pk_mul_f32 v[52:53], v[52:53], s[84:85] op_sel_hi:[1,0]
	v_lshl_add_u64 v[74:75], v[68:69], 0, v[0:1]
	v_pk_mul_f32 v[52:53], v[56:57], v[52:53]
	v_cvt_pk_bf16_f32 v73, v54, v55
	v_cvt_pk_bf16_f32 v54, v58, v59
	v_cvt_pk_bf16_f32 v55, v60, v61
	v_cvt_pk_bf16_f32 v56, v50, v51
	v_cvt_pk_bf16_f32 v57, v52, v53
	global_store_dwordx4 v[74:75], v[70:73], off
	global_store_dwordx4 v[74:75], v[54:57], off offset:64
	v_mov_b32_e32 v50, v162
	s_nop 0
	v_ashrrev_i32_e32 v51, 31, v50
	v_lshl_add_u64 v[50:51], v[50:51], 4, s[10:11]
	s_waitcnt vmcnt(12)
; DI void st8(bf16_t* dst, const float (&v)[8]) { u32x4 o = {pk2(v[0], v[1]), pk2(v[2], v[3]), pk2(v[4], v[5]), pk2(v[6], v[7])}; *(u32x4*)dst = o; }
; DI float dq8(unsigned w, int k) { return (float)((w >> (8 * k)) & 255u) * (1.f / 255.f); }
; DI u32x4* gate_slot(const Params& P, int tile, int j, int g8) { return (u32x4*)slotp(P, SL_SK) + ((size_t)(tile * 3 + j) * 8 + g8) * 512 + tid(); }
; DI void merge_final(const Params& P, int tile, bf16_t* __restrict__ hb, const f32x4 (&acc)[2][2][4][2], int m0, int n0) {
;     ...
;             for (int nn = 0; nn < 2; ++nn) {
;                 const size_t tok = (size_t)m0 + bj * 128 + wc * 32 + nn * 16 + fr;
;                 const int col = n0 + ai * 128 + wr * 64 + 8 * fq;
;                 float lo[8], hi[8];
;                 grp16(acc, ai, bj, nn, 1.f, lo, hi);
;                 const u32x4 gq = *gate_slot(P, tile, 2, ai * 4 + bj * 2 + nn);
; #pragma unroll
;                 for (int e = 0; e < 8; ++e) { lo[e] *= dq8(gq[e >> 2], e & 3); hi[e] *= dq8(gq[2 + (e >> 2)], e & 3); }
;                 bf16_t* hp = hb + tok * 1024 + col;
;                 st8(hp, lo); st8(hp + 32, hi);
;                 __builtin_amdgcn_sched_barrier(0);
;             }
; DI void merge_phase(const Params& P, int layer, char* lds) {
;     ...
;     for (int t = blockIdx.x; t < 128 * 4; t += gridDim.x) {
	s_nop 1
	v_mov_b64_e32 v[52:53], v[204:205]
	v_mov_b64_e32 v[54:55], v[206:207]
	v_cvt_f32_ubyte1_e32 v51, v52
	v_cvt_f32_ubyte0_e32 v50, v52
	v_pk_mul_f32 v[50:51], v[50:51], s[84:85] op_sel_hi:[1,0]
	s_nop 0
	v_pk_mul_f32 v[50:51], v[42:43], v[50:51]
	v_cvt_f32_ubyte1_e32 v43, v54
	v_cvt_f32_ubyte0_e32 v42, v54
	v_pk_mul_f32 v[42:43], v[42:43], s[84:85] op_sel_hi:[1,0]
	v_cvt_pk_bf16_f32 v50, v50, v51
	v_pk_mul_f32 v[42:43], v[46:47], v[42:43]
	v_cvt_f32_ubyte3_e32 v47, v52
	v_cvt_f32_ubyte2_e32 v46, v52
	v_pk_mul_f32 v[46:47], v[46:47], s[84:85] op_sel_hi:[1,0]
	s_nop 0
	v_pk_mul_f32 v[46:47], v[44:45], v[46:47]
	v_cvt_f32_ubyte3_e32 v45, v54
	v_cvt_f32_ubyte2_e32 v44, v54
	v_pk_mul_f32 v[44:45], v[44:45], s[84:85] op_sel_hi:[1,0]
	v_cvt_pk_bf16_f32 v51, v46, v47
	v_pk_mul_f32 v[44:45], v[48:49], v[44:45]
	v_cvt_f32_ubyte1_e32 v49, v53
	v_cvt_f32_ubyte0_e32 v48, v53
	v_pk_mul_f32 v[48:49], v[48:49], s[84:85] op_sel_hi:[1,0]
	s_nop 0
	v_pk_mul_f32 v[48:49], v[34:35], v[48:49]
	v_cvt_f32_ubyte1_e32 v35, v55
	v_cvt_f32_ubyte0_e32 v34, v55
	v_pk_mul_f32 v[34:35], v[34:35], s[84:85] op_sel_hi:[1,0]
	v_cvt_pk_bf16_f32 v52, v48, v49
	v_pk_mul_f32 v[34:35], v[38:39], v[34:35]
	v_cvt_f32_ubyte3_e32 v39, v53
	v_cvt_f32_ubyte2_e32 v38, v53
	v_pk_mul_f32 v[38:39], v[38:39], s[84:85] op_sel_hi:[1,0]
	s_nop 0
	v_pk_mul_f32 v[38:39], v[36:37], v[38:39]
	v_cvt_f32_ubyte3_e32 v37, v55
	v_cvt_f32_ubyte2_e32 v36, v55
	v_pk_mul_f32 v[36:37], v[36:37], s[84:85] op_sel_hi:[1,0]
	v_lshl_add_u64 v[54:55], v[68:69], 0, v[98:99]
	v_pk_mul_f32 v[36:37], v[40:41], v[36:37]
	v_cvt_pk_bf16_f32 v53, v38, v39
	v_cvt_pk_bf16_f32 v38, v42, v43
	v_cvt_pk_bf16_f32 v39, v44, v45
	v_cvt_pk_bf16_f32 v40, v34, v35
	v_cvt_pk_bf16_f32 v41, v36, v37
	global_store_dwordx4 v[54:55], v[50:53], off
	global_store_dwordx4 v[54:55], v[38:41], off offset:64
	v_mov_b32_e32 v34, v162
	s_nop 0
	v_ashrrev_i32_e32 v35, 31, v34
	v_lshl_add_u64 v[34:35], v[34:35], 4, s[12:13]
	s_waitcnt vmcnt(13)
	s_nop 1
	v_mov_b64_e32 v[36:37], v[208:209]
	v_mov_b64_e32 v[38:39], v[210:211]
	v_cvt_f32_ubyte1_e32 v35, v36
	v_cvt_f32_ubyte0_e32 v34, v36
	v_pk_mul_f32 v[34:35], v[34:35], s[84:85] op_sel_hi:[1,0]
	s_nop 0
	v_pk_mul_f32 v[34:35], v[26:27], v[34:35]
	v_cvt_f32_ubyte1_e32 v27, v38
	v_cvt_f32_ubyte0_e32 v26, v38
	v_pk_mul_f32 v[26:27], v[26:27], s[84:85] op_sel_hi:[1,0]
	v_cvt_pk_bf16_f32 v34, v34, v35
	v_pk_mul_f32 v[26:27], v[30:31], v[26:27]
	v_cvt_f32_ubyte3_e32 v31, v36
	v_cvt_f32_ubyte2_e32 v30, v36
	v_pk_mul_f32 v[30:31], v[30:31], s[84:85] op_sel_hi:[1,0]
	s_nop 0
	v_pk_mul_f32 v[30:31], v[28:29], v[30:31]
	v_cvt_f32_ubyte3_e32 v29, v38
	v_cvt_f32_ubyte2_e32 v28, v38
	v_pk_mul_f32 v[28:29], v[28:29], s[84:85] op_sel_hi:[1,0]
	v_cvt_pk_bf16_f32 v35, v30, v31
	v_pk_mul_f32 v[28:29], v[32:33], v[28:29]
	v_cvt_f32_ubyte1_e32 v33, v37
	v_cvt_f32_ubyte0_e32 v32, v37
	v_pk_mul_f32 v[32:33], v[32:33], s[84:85] op_sel_hi:[1,0]
	s_nop 0
	v_pk_mul_f32 v[32:33], v[18:19], v[32:33]
	v_cvt_f32_ubyte1_e32 v19, v39
	v_cvt_f32_ubyte0_e32 v18, v39
	v_pk_mul_f32 v[18:19], v[18:19], s[84:85] op_sel_hi:[1,0]
	v_cvt_pk_bf16_f32 v36, v32, v33
	v_pk_mul_f32 v[18:19], v[22:23], v[18:19]
	v_cvt_f32_ubyte3_e32 v23, v37
	v_cvt_f32_ubyte2_e32 v22, v37
	v_pk_mul_f32 v[22:23], v[22:23], s[84:85] op_sel_hi:[1,0]
	s_nop 0
	v_pk_mul_f32 v[22:23], v[20:21], v[22:23]
	v_cvt_f32_ubyte3_e32 v21, v39
	v_cvt_f32_ubyte2_e32 v20, v39
	v_pk_mul_f32 v[20:21], v[20:21], s[84:85] op_sel_hi:[1,0]
	v_lshl_add_u64 v[38:39], v[68:69], 0, v[82:83]
	v_pk_mul_f32 v[20:21], v[24:25], v[20:21]
	v_cvt_pk_bf16_f32 v37, v22, v23
	v_cvt_pk_bf16_f32 v22, v26, v27
	v_cvt_pk_bf16_f32 v23, v28, v29
	v_cvt_pk_bf16_f32 v24, v18, v19
	v_cvt_pk_bf16_f32 v25, v20, v21
	global_store_dwordx4 v[38:39], v[34:37], off
	global_store_dwordx4 v[38:39], v[22:25], off offset:64
	v_mov_b32_e32 v18, v162
	s_nop 0
	v_ashrrev_i32_e32 v19, 31, v18
	v_lshl_add_u64 v[18:19], v[18:19], 4, s[16:17]
	s_waitcnt vmcnt(14)
	s_nop 1
	v_mov_b64_e32 v[20:21], v[212:213]
	v_mov_b64_e32 v[22:23], v[214:215]
	v_cvt_f32_ubyte1_e32 v19, v20
	v_cvt_f32_ubyte0_e32 v18, v20
	v_pk_mul_f32 v[18:19], v[18:19], s[84:85] op_sel_hi:[1,0]
	s_nop 0
	v_pk_mul_f32 v[18:19], v[10:11], v[18:19]
	v_cvt_f32_ubyte1_e32 v11, v22
	v_cvt_f32_ubyte0_e32 v10, v22
	v_pk_mul_f32 v[10:11], v[10:11], s[84:85] op_sel_hi:[1,0]
	v_cvt_pk_bf16_f32 v18, v18, v19
	v_pk_mul_f32 v[10:11], v[14:15], v[10:11]
	v_cvt_f32_ubyte3_e32 v15, v20
	v_cvt_f32_ubyte2_e32 v14, v20
	v_pk_mul_f32 v[14:15], v[14:15], s[84:85] op_sel_hi:[1,0]
	s_nop 0
	v_pk_mul_f32 v[14:15], v[12:13], v[14:15]
	v_cvt_f32_ubyte3_e32 v13, v22
	v_cvt_f32_ubyte2_e32 v12, v22
	v_pk_mul_f32 v[12:13], v[12:13], s[84:85] op_sel_hi:[1,0]
	v_cvt_pk_bf16_f32 v19, v14, v15
	v_pk_mul_f32 v[12:13], v[16:17], v[12:13]
	v_cvt_f32_ubyte1_e32 v17, v21
	v_cvt_f32_ubyte0_e32 v16, v21
	v_pk_mul_f32 v[16:17], v[16:17], s[84:85] op_sel_hi:[1,0]
	s_nop 0
	v_pk_mul_f32 v[16:17], v[2:3], v[16:17]
	v_cvt_f32_ubyte1_e32 v3, v23
	v_cvt_f32_ubyte0_e32 v2, v23
	v_pk_mul_f32 v[2:3], v[2:3], s[84:85] op_sel_hi:[1,0]
	v_cvt_pk_bf16_f32 v20, v16, v17
	v_pk_mul_f32 v[2:3], v[6:7], v[2:3]
	v_cvt_f32_ubyte3_e32 v7, v21
	v_cvt_f32_ubyte2_e32 v6, v21
	v_pk_mul_f32 v[6:7], v[6:7], s[84:85] op_sel_hi:[1,0]
	s_nop 0
	v_pk_mul_f32 v[6:7], v[4:5], v[6:7]
	v_cvt_f32_ubyte3_e32 v5, v23
	v_cvt_f32_ubyte2_e32 v4, v23
	v_pk_mul_f32 v[4:5], v[4:5], s[84:85] op_sel_hi:[1,0]
	v_lshl_add_u64 v[22:23], v[68:69], 0, v[66:67]
	v_pk_mul_f32 v[4:5], v[8:9], v[4:5]
	v_cvt_pk_bf16_f32 v21, v6, v7
	v_cvt_pk_bf16_f32 v6, v10, v11
	v_cvt_pk_bf16_f32 v7, v12, v13
	v_cvt_pk_bf16_f32 v8, v2, v3
	v_cvt_pk_bf16_f32 v9, v4, v5
	global_store_dwordx4 v[22:23], v[18:21], off
	global_store_dwordx4 v[22:23], v[6:9], off offset:64
	v_readlane_b32 s2, v253, 30
	v_readlane_b32 s3, v253, 31
	s_load_dword s2, s[2:3], 0x0
	s_waitcnt lgkmcnt(0)
	s_add_i32 s28, s2, s28
	s_cmpk_gt_i32 s28, 0x1ff
	s_cbranch_scc1 .LBB0_63

; #define STAGE(P, BASE, br, kt) do { const bf16_t* g_ = (BASE) + (size_t)(br) * K + (size_t)(kt) * 64; \
;         _Pragma("unroll") for (int i_ = 0; i_ < 2; ++i_) \
;             __builtin_amdgcn_global_load_lds((const unsigned*)(g_ + gofs[i_]), (lds_ptr_t)((P) + wb + i_ * 8192), 16, 0, 0); } while (0)
; #define LDA(dst, b, hh) _Pragma("unroll") for (int m = 0; m < 4; ++m) _Pragma("unroll") for (int k = 0; k < 2; ++k) \
;         dst[m][k] = *(const bf16x8*)(SA(b, hh) + lds_byte(wr * 64 + m * 16 + fr, k * 32 + fq * 8))
; #define LDB(dst, b, hh) _Pragma("unroll") for (int n = 0; n < 2; ++n) _Pragma("unroll") for (int k = 0; k < 2; ++k) \
;         dst[n][k] = *(const bf16x8*)(SB(b, hh) + lds_byte(wc * 32 + n * 16 + fr, k * 32 + fq * 8))
; #define MMA(ai, bj, At_, Bt_) do { __builtin_amdgcn_s_setprio(1); \
;         _Pragma("unroll") for (int m = 0; m < 4; ++m) _Pragma("unroll") for (int n = 0; n < 2; ++n) _Pragma("unroll") for (int k = 0; k < 2; ++k) \
;             acc[ai][bj][m][n] = MFMA16(At_[m][k], Bt_[n][k], acc[ai][bj][m][n]); \
;         __builtin_amdgcn_s_setprio(0); } while (0)
; #define WAIT_V(n) asm volatile("s_waitcnt vmcnt(" #n ")" ::: "memory")
; #define BAR __builtin_amdgcn_s_barrier()
; template <class Hook>
; DI void gemm8_cat3(f32x4 (&acc)[2][2][4][2], const bf16_t* R0, const bf16_t* R1, const bf16_t* R2, const bf16_t* C0, const bf16_t* C1, const bf16_t* C2, char* shm, Hook hook) {
;     ...
;     for (int tt = 0; tt < 8; tt += 2) {
;         LDB(B0, 0, 0); SCHED; LDA(At, 0, 0); STAGE(SA(1, 1), R, 128, tt + 1);
;         WAIT_L(8); BAR; WAIT_L(0); MMA(0, 0, At, B0); BAR; SCHED;
;         LDB(B1, 0, 1); STAGE(SB(0, 0), C, 0, tt + 2);
;         BAR; WAIT_L(0); MMA(0, 1, At, B1); BAR;
;         LDA(At, 0, 1); STAGE(SA(0, 0), R, 0, tt + 2);
;         BAR; WAIT_L(0); MMA(1, 0, At, B0); BAR; SCHED;
;         STAGE(SB(0, 1), C, 128, tt + 2);
;         WAIT_V(6); BAR; MMA(1, 1, At, B1); BAR;
;         LDB(B0, 1, 0); SCHED; LDA(At, 1, 0); STAGE(SA(0, 1), R, 128, tt + 2);
;         WAIT_L(8); BAR; WAIT_L(0); MMA(0, 0, At, B0); BAR; SCHED;
;         LDB(B1, 1, 1); STAGE(SB(1, 0), C, 0, tt + 3);
;         BAR; WAIT_L(0); MMA(0, 1, At, B1); BAR;
;         LDA(At, 1, 1); STAGE(SA(1, 0), R, 0, tt + 3);
;         BAR; WAIT_L(0); MMA(1, 0, At, B0); BAR; SCHED;
;         STAGE(SB(1, 1), C, 128, tt + 3);
;         WAIT_V(6); BAR; MMA(1, 1, At, B1); BAR;
;     }
.LBB0_56:
	ds_read_b128 v[150:153], v189
	ds_read_b128 v[192:195], v189 offset:1024
	ds_read_b128 v[196:199], v189 offset:2048
	ds_read_b128 v[200:203], v189 offset:3072
	v_add_u32_e32 v190, 0xc000, v158
	v_add_u32_e32 v191, 0xe000, v158
	v_readfirstlane_b32 s7, v190
	s_mov_b32 m0, s7
	v_readfirstlane_b32 s7, v191
	ds_read_b128 v[204:207], v157
	ds_read_b128 v[208:211], v157 offset:1024
	ds_read_b128 v[212:215], v156
	ds_read_b128 v[216:219], v156 offset:1024
	ds_read_b128 v[220:223], v155
	ds_read_b128 v[224:227], v155 offset:1024
	ds_read_b128 v[228:231], v154
	ds_read_b128 v[232:235], v154 offset:1024
	global_load_lds_dwordx4 v[130:131], off
	s_mov_b32 m0, s7
	s_nop 0
	global_load_lds_dwordx4 v[132:133], off
	s_waitcnt lgkmcnt(8)
	s_barrier
	s_waitcnt lgkmcnt(0)
	s_setprio 1
	s_waitcnt lgkmcnt(0)
	v_mfma_f32_16x16x32_bf16 v[18:21], v[204:207], v[150:153], v[18:21]
	v_mfma_f32_16x16x32_bf16 v[58:61], v[204:207], v[196:199], v[58:61]
	v_mfma_f32_16x16x32_bf16 v[30:33], v[212:215], v[150:153], v[30:33]
	v_mfma_f32_16x16x32_bf16 v[54:57], v[212:215], v[196:199], v[54:57]
	v_mfma_f32_16x16x32_bf16 v[26:29], v[220:223], v[150:153], v[26:29]
	v_mfma_f32_16x16x32_bf16 v[50:53], v[220:223], v[196:199], v[50:53]
	v_mfma_f32_16x16x32_bf16 v[42:45], v[228:231], v[150:153], v[42:45]
	v_mfma_f32_16x16x32_bf16 v[46:49], v[228:231], v[196:199], v[46:49]
	v_mfma_f32_16x16x32_bf16 v[18:21], v[208:211], v[192:195], v[18:21]
	v_mfma_f32_16x16x32_bf16 v[58:61], v[208:211], v[200:203], v[58:61]
	v_mfma_f32_16x16x32_bf16 v[30:33], v[216:219], v[192:195], v[30:33]
	v_mfma_f32_16x16x32_bf16 v[54:57], v[216:219], v[200:203], v[54:57]
	v_mfma_f32_16x16x32_bf16 v[26:29], v[224:227], v[192:195], v[26:29]
	v_mfma_f32_16x16x32_bf16 v[50:53], v[224:227], v[200:203], v[50:53]
	v_mfma_f32_16x16x32_bf16 v[42:45], v[232:235], v[192:195], v[42:45]
	v_mfma_f32_16x16x32_bf16 v[46:49], v[232:235], v[200:203], v[46:49]
	s_setprio 0
	s_barrier
	s_add_i32 s7, s6, 2
	s_cmp_lt_u32 s6, 6
	s_cselect_b64 s[16:17], -1, 0
	s_and_b64 s[20:21], s[16:17], exec
	s_cselect_b32 s21, s11, s82
	s_cselect_b32 s20, s10, s25
	s_and_b32 s22, s2, 0x180
	s_lshl_b32 s22, s22, 1
	s_add_u32 s20, s20, s22
	s_addc_u32 s21, s21, 0
	v_readfirstlane_b32 s23, v159
	v_lshl_add_u64 v[172:173], s[20:21], 0, v[134:135]
	s_mov_b32 m0, s23
	v_readfirstlane_b32 s23, v160
	ds_read_b128 v[236:239], v188
	ds_read_b128 v[240:243], v188 offset:1024
	ds_read_b128 v[244:247], v188 offset:2048
	ds_read_b128 v[248:251], v188 offset:3072
	global_load_lds_dwordx4 v[172:173], off
	v_lshl_add_u64 v[172:173], s[20:21], 0, v[136:137]
	s_mov_b32 m0, s23
	s_nop 0
	global_load_lds_dwordx4 v[172:173], off
	s_barrier
	s_waitcnt lgkmcnt(0)
	s_setprio 1
	s_waitcnt lgkmcnt(0)
	v_mfma_f32_16x16x32_bf16 v[74:77], v[204:207], v[236:239], v[74:77]
	v_mfma_f32_16x16x32_bf16 v[90:93], v[204:207], v[244:247], v[90:93]
	v_mfma_f32_16x16x32_bf16 v[70:73], v[212:215], v[236:239], v[70:73]
	v_mfma_f32_16x16x32_bf16 v[86:89], v[212:215], v[244:247], v[86:89]
	v_mfma_f32_16x16x32_bf16 v[66:69], v[220:223], v[236:239], v[66:69]
	v_mfma_f32_16x16x32_bf16 v[82:85], v[220:223], v[244:247], v[82:85]
	v_mfma_f32_16x16x32_bf16 v[62:65], v[228:231], v[236:239], v[62:65]
	v_mfma_f32_16x16x32_bf16 v[78:81], v[228:231], v[244:247], v[78:81]
	v_mfma_f32_16x16x32_bf16 v[74:77], v[208:211], v[240:243], v[74:77]
	v_mfma_f32_16x16x32_bf16 v[90:93], v[208:211], v[248:251], v[90:93]
	v_mfma_f32_16x16x32_bf16 v[70:73], v[216:219], v[240:243], v[70:73]
	v_mfma_f32_16x16x32_bf16 v[86:89], v[216:219], v[248:251], v[86:89]
	v_mfma_f32_16x16x32_bf16 v[66:69], v[224:227], v[240:243], v[66:69]
	v_mfma_f32_16x16x32_bf16 v[82:85], v[224:227], v[248:251], v[82:85]
	v_mfma_f32_16x16x32_bf16 v[62:65], v[232:235], v[240:243], v[62:65]
	v_mfma_f32_16x16x32_bf16 v[78:81], v[232:235], v[248:251], v[78:81]
	s_setprio 0
	s_and_b64 vcc, s[16:17], exec
	s_cselect_b32 s16, s8, s15
	s_cselect_b32 s17, s9, s24
	s_add_u32 s16, s16, s22
	s_addc_u32 s17, s17, 0
	v_readfirstlane_b32 s22, v158
	v_lshl_add_u64 v[172:173], s[16:17], 0, v[134:135]
	s_mov_b32 m0, s22
	v_readfirstlane_b32 s22, v164
	s_barrier
	ds_read_b128 v[204:207], v157 offset:16384
	ds_read_b128 v[208:211], v157 offset:17408
	ds_read_b128 v[212:215], v156 offset:16384
	ds_read_b128 v[216:219], v156 offset:17408
	ds_read_b128 v[220:223], v155 offset:16384
	ds_read_b128 v[224:227], v155 offset:17408
	ds_read_b128 v[228:231], v154 offset:16384
	ds_read_b128 v[232:235], v154 offset:17408
	global_load_lds_dwordx4 v[172:173], off
	v_lshl_add_u64 v[172:173], s[16:17], 0, v[136:137]
	s_mov_b32 m0, s22
	s_nop 0
	global_load_lds_dwordx4 v[172:173], off
	s_barrier
	s_waitcnt lgkmcnt(0)
	s_setprio 1
	s_waitcnt lgkmcnt(0)
	v_mfma_f32_16x16x32_bf16 v[106:109], v[204:207], v[150:153], v[106:109]
	v_mfma_f32_16x16x32_bf16 v[122:125], v[204:207], v[196:199], v[122:125]
	v_mfma_f32_16x16x32_bf16 v[102:105], v[212:215], v[150:153], v[102:105]
	v_mfma_f32_16x16x32_bf16 v[118:121], v[212:215], v[196:199], v[118:121]
	v_mfma_f32_16x16x32_bf16 v[98:101], v[220:223], v[150:153], v[98:101]
	v_mfma_f32_16x16x32_bf16 v[114:117], v[220:223], v[196:199], v[114:117]
	v_mfma_f32_16x16x32_bf16 v[94:97], v[228:231], v[150:153], v[94:97]
	v_mfma_f32_16x16x32_bf16 v[110:113], v[228:231], v[196:199], v[110:113]
	v_mfma_f32_16x16x32_bf16 v[106:109], v[208:211], v[192:195], v[106:109]
	v_mfma_f32_16x16x32_bf16 v[122:125], v[208:211], v[200:203], v[122:125]
	v_mfma_f32_16x16x32_bf16 v[102:105], v[216:219], v[192:195], v[102:105]
	v_mfma_f32_16x16x32_bf16 v[118:121], v[216:219], v[200:203], v[118:121]
	v_mfma_f32_16x16x32_bf16 v[98:101], v[224:227], v[192:195], v[98:101]
	v_mfma_f32_16x16x32_bf16 v[114:117], v[224:227], v[200:203], v[114:117]
	v_mfma_f32_16x16x32_bf16 v[94:97], v[232:235], v[192:195], v[94:97]
	v_mfma_f32_16x16x32_bf16 v[110:113], v[232:235], v[200:203], v[110:113]
	s_setprio 0
	s_barrier
; #define STAGE(P, BASE, br, kt) do { const bf16_t* g_ = (BASE) + (size_t)(br) * K + (size_t)(kt) * 64; \
;         _Pragma("unroll") for (int i_ = 0; i_ < 2; ++i_) \
;             __builtin_amdgcn_global_load_lds((const unsigned*)(g_ + gofs[i_]), (lds_ptr_t)((P) + wb + i_ * 8192), 16, 0, 0); } while (0)
; #define LDA(dst, b, hh) _Pragma("unroll") for (int m = 0; m < 4; ++m) _Pragma("unroll") for (int k = 0; k < 2; ++k) \
;         dst[m][k] = *(const bf16x8*)(SA(b, hh) + lds_byte(wr * 64 + m * 16 + fr, k * 32 + fq * 8))
; #define LDB(dst, b, hh) _Pragma("unroll") for (int n = 0; n < 2; ++n) _Pragma("unroll") for (int k = 0; k < 2; ++k) \
;         dst[n][k] = *(const bf16x8*)(SB(b, hh) + lds_byte(wc * 32 + n * 16 + fr, k * 32 + fq * 8))
; #define MMA(ai, bj, At_, Bt_) do { __builtin_amdgcn_s_setprio(1); \
;         _Pragma("unroll") for (int m = 0; m < 4; ++m) _Pragma("unroll") for (int n = 0; n < 2; ++n) _Pragma("unroll") for (int k = 0; k < 2; ++k) \
;             acc[ai][bj][m][n] = MFMA16(At_[m][k], Bt_[n][k], acc[ai][bj][m][n]); \
;         __builtin_amdgcn_s_setprio(0); } while (0)
; #define WAIT_V(n) asm volatile("s_waitcnt vmcnt(" #n ")" ::: "memory")
; #define BAR __builtin_amdgcn_s_barrier()
; template <class Hook>
; DI void gemm8_cat3(f32x4 (&acc)[2][2][4][2], const bf16_t* R0, const bf16_t* R1, const bf16_t* R2, const bf16_t* C0, const bf16_t* C1, const bf16_t* C2, char* shm, Hook hook) {
;     ...
;     for (int tt = 0; tt < 8; tt += 2) {
;         LDB(B0, 0, 0); SCHED; LDA(At, 0, 0); STAGE(SA(1, 1), R, 128, tt + 1);
;         WAIT_L(8); BAR; WAIT_L(0); MMA(0, 0, At, B0); BAR; SCHED;
;         LDB(B1, 0, 1); STAGE(SB(0, 0), C, 0, tt + 2);
;         BAR; WAIT_L(0); MMA(0, 1, At, B1); BAR;
;         LDA(At, 0, 1); STAGE(SA(0, 0), R, 0, tt + 2);
;         BAR; WAIT_L(0); MMA(1, 0, At, B0); BAR; SCHED;
;         STAGE(SB(0, 1), C, 128, tt + 2);
;         WAIT_V(6); BAR; MMA(1, 1, At, B1); BAR;
;         LDB(B0, 1, 0); SCHED; LDA(At, 1, 0); STAGE(SA(0, 1), R, 128, tt + 2);
;         WAIT_L(8); BAR; WAIT_L(0); MMA(0, 0, At, B0); BAR; SCHED;
;         LDB(B1, 1, 1); STAGE(SB(1, 0), C, 0, tt + 3);
;         BAR; WAIT_L(0); MMA(0, 1, At, B1); BAR;
;         LDA(At, 1, 1); STAGE(SA(1, 0), R, 0, tt + 3);
;         BAR; WAIT_L(0); MMA(1, 0, At, B0); BAR; SCHED;
;         STAGE(SB(1, 1), C, 128, tt + 3);
;         WAIT_V(6); BAR; MMA(1, 1, At, B1); BAR;
;     }
	s_add_u32 s20, s20, 0x20000
	s_addc_u32 s21, s21, 0
	v_readfirstlane_b32 s22, v165
	v_lshl_add_u64 v[150:151], s[20:21], 0, v[134:135]
	s_mov_b32 m0, s22
	s_nop 0
	global_load_lds_dwordx4 v[150:151], off
	v_lshl_add_u64 v[150:151], s[20:21], 0, v[136:137]
	v_readfirstlane_b32 s20, v166
	s_mov_b32 m0, s20
	s_nop 0
	global_load_lds_dwordx4 v[150:151], off
	s_waitcnt vmcnt(6)
	s_barrier
	s_setprio 1
	v_mfma_f32_16x16x32_bf16 v[126:129], v[204:207], v[236:239], v[126:129]
	v_mfma_f32_16x16x32_bf16 v[14:17], v[204:207], v[244:247], v[14:17]
	v_mfma_f32_16x16x32_bf16 v[34:37], v[212:215], v[236:239], v[34:37]
	v_mfma_f32_16x16x32_bf16 v[6:9], v[212:215], v[244:247], v[6:9]
	v_mfma_f32_16x16x32_bf16 v[38:41], v[220:223], v[236:239], v[38:41]
	v_mfma_f32_16x16x32_bf16 v[10:13], v[220:223], v[244:247], v[10:13]
	v_mfma_f32_16x16x32_bf16 v[22:25], v[228:231], v[236:239], v[22:25]
	v_mfma_f32_16x16x32_bf16 v[2:5], v[228:231], v[244:247], v[2:5]
	v_mfma_f32_16x16x32_bf16 v[126:129], v[208:211], v[240:243], v[126:129]
	v_mfma_f32_16x16x32_bf16 v[14:17], v[208:211], v[248:251], v[14:17]
	v_mfma_f32_16x16x32_bf16 v[34:37], v[216:219], v[240:243], v[34:37]
	v_mfma_f32_16x16x32_bf16 v[6:9], v[216:219], v[248:251], v[6:9]
	v_mfma_f32_16x16x32_bf16 v[38:41], v[224:227], v[240:243], v[38:41]
	v_mfma_f32_16x16x32_bf16 v[10:13], v[224:227], v[248:251], v[10:13]
	v_mfma_f32_16x16x32_bf16 v[22:25], v[232:235], v[240:243], v[22:25]
	v_mfma_f32_16x16x32_bf16 v[2:5], v[232:235], v[248:251], v[2:5]
	s_setprio 0
	s_barrier
	ds_read_b128 v[150:153], v169
	ds_read_b128 v[192:195], v169 offset:1024
	ds_read_b128 v[196:199], v169 offset:2048
	ds_read_b128 v[200:203], v169 offset:3072
	s_add_u32 s16, s16, 0x20000
	s_addc_u32 s17, s17, 0
	v_readfirstlane_b32 s20, v167
	v_lshl_add_u64 v[172:173], s[16:17], 0, v[134:135]
	s_mov_b32 m0, s20
	ds_read_b128 v[204:207], v157 offset:32768
	ds_read_b128 v[208:211], v157 offset:33792
	ds_read_b128 v[212:215], v156 offset:32768
	ds_read_b128 v[216:219], v156 offset:33792
	ds_read_b128 v[220:223], v155 offset:32768
	ds_read_b128 v[224:227], v155 offset:33792
	ds_read_b128 v[228:231], v154 offset:32768
	ds_read_b128 v[232:235], v154 offset:33792
	global_load_lds_dwordx4 v[172:173], off
	v_lshl_add_u64 v[172:173], s[16:17], 0, v[136:137]
	v_readfirstlane_b32 s16, v168
	s_mov_b32 m0, s16
	s_nop 0
	global_load_lds_dwordx4 v[172:173], off
	s_waitcnt lgkmcnt(8)
	s_barrier
	s_waitcnt lgkmcnt(0)
	s_setprio 1
	s_waitcnt lgkmcnt(0)
	v_mfma_f32_16x16x32_bf16 v[18:21], v[204:207], v[150:153], v[18:21]
	v_mfma_f32_16x16x32_bf16 v[58:61], v[204:207], v[196:199], v[58:61]
	v_mfma_f32_16x16x32_bf16 v[30:33], v[212:215], v[150:153], v[30:33]
	v_mfma_f32_16x16x32_bf16 v[54:57], v[212:215], v[196:199], v[54:57]
	v_mfma_f32_16x16x32_bf16 v[26:29], v[220:223], v[150:153], v[26:29]
	v_mfma_f32_16x16x32_bf16 v[50:53], v[220:223], v[196:199], v[50:53]
	v_mfma_f32_16x16x32_bf16 v[42:45], v[228:231], v[150:153], v[42:45]
	v_mfma_f32_16x16x32_bf16 v[46:49], v[228:231], v[196:199], v[46:49]
	v_mfma_f32_16x16x32_bf16 v[18:21], v[208:211], v[192:195], v[18:21]
	v_mfma_f32_16x16x32_bf16 v[58:61], v[208:211], v[200:203], v[58:61]
	v_mfma_f32_16x16x32_bf16 v[30:33], v[216:219], v[192:195], v[30:33]
	v_mfma_f32_16x16x32_bf16 v[54:57], v[216:219], v[200:203], v[54:57]
	v_mfma_f32_16x16x32_bf16 v[26:29], v[224:227], v[192:195], v[26:29]
	v_mfma_f32_16x16x32_bf16 v[50:53], v[224:227], v[200:203], v[50:53]
	v_mfma_f32_16x16x32_bf16 v[42:45], v[232:235], v[192:195], v[42:45]
	v_mfma_f32_16x16x32_bf16 v[46:49], v[232:235], v[200:203], v[46:49]
	s_setprio 0
	s_barrier
	s_add_i32 s16, s2, 64
	s_and_b32 s16, s16, 0x1c0
	s_lshl_b32 s20, s16, 1
	s_cmp_lt_u32 s6, 5
	s_cselect_b32 s16, s10, s25
	s_cselect_b32 s6, s11, s82
	s_cselect_b32 s21, s9, s24
	s_cselect_b32 s22, s8, s15
	s_add_u32 s16, s16, s20
	s_addc_u32 s17, s6, 0
	v_readfirstlane_b32 s6, v170
	v_lshl_add_u64 v[172:173], s[16:17], 0, v[134:135]
	s_mov_b32 m0, s6
	v_readfirstlane_b32 s6, v171
	ds_read_b128 v[236:239], v161
	ds_read_b128 v[240:243], v161 offset:1024
	ds_read_b128 v[244:247], v161 offset:2048
	ds_read_b128 v[248:251], v161 offset:3072
	global_load_lds_dwordx4 v[172:173], off
	v_lshl_add_u64 v[172:173], s[16:17], 0, v[136:137]
	s_mov_b32 m0, s6
	s_nop 0
	global_load_lds_dwordx4 v[172:173], off
	s_barrier
	s_waitcnt lgkmcnt(0)
	s_setprio 1
	s_waitcnt lgkmcnt(0)
	v_mfma_f32_16x16x32_bf16 v[74:77], v[204:207], v[236:239], v[74:77]
	v_mfma_f32_16x16x32_bf16 v[90:93], v[204:207], v[244:247], v[90:93]
	v_mfma_f32_16x16x32_bf16 v[70:73], v[212:215], v[236:239], v[70:73]
	v_mfma_f32_16x16x32_bf16 v[86:89], v[212:215], v[244:247], v[86:89]
	v_mfma_f32_16x16x32_bf16 v[66:69], v[220:223], v[236:239], v[66:69]
	v_mfma_f32_16x16x32_bf16 v[82:85], v[220:223], v[244:247], v[82:85]
	v_mfma_f32_16x16x32_bf16 v[62:65], v[228:231], v[236:239], v[62:65]
	v_mfma_f32_16x16x32_bf16 v[78:81], v[228:231], v[244:247], v[78:81]
	v_mfma_f32_16x16x32_bf16 v[74:77], v[208:211], v[240:243], v[74:77]
	v_mfma_f32_16x16x32_bf16 v[90:93], v[208:211], v[248:251], v[90:93]
	v_mfma_f32_16x16x32_bf16 v[70:73], v[216:219], v[240:243], v[70:73]
	v_mfma_f32_16x16x32_bf16 v[86:89], v[216:219], v[248:251], v[86:89]
	v_mfma_f32_16x16x32_bf16 v[66:69], v[224:227], v[240:243], v[66:69]
	v_mfma_f32_16x16x32_bf16 v[82:85], v[224:227], v[248:251], v[82:85]
	v_mfma_f32_16x16x32_bf16 v[62:65], v[232:235], v[240:243], v[62:65]
	v_mfma_f32_16x16x32_bf16 v[78:81], v[232:235], v[248:251], v[78:81]
	s_setprio 0
	s_add_u32 s20, s22, s20
	s_addc_u32 s21, s21, 0
	v_readfirstlane_b32 s6, v184
	v_lshl_add_u64 v[172:173], s[20:21], 0, v[134:135]
	s_mov_b32 m0, s6
	v_readfirstlane_b32 s6, v185
	s_barrier
; DI float frcp(float x) { return __builtin_amdgcn_rcpf(x); }
; #define STAGE(P, BASE, br, kt) do { const bf16_t* g_ = (BASE) + (size_t)(br) * K + (size_t)(kt) * 64; \
;         _Pragma("unroll") for (int i_ = 0; i_ < 2; ++i_) \
;             __builtin_amdgcn_global_load_lds((const unsigned*)(g_ + gofs[i_]), (lds_ptr_t)((P) + wb + i_ * 8192), 16, 0, 0); } while (0)
; #define MMA(ai, bj, At_, Bt_) do { __builtin_amdgcn_s_setprio(1); \
;         _Pragma("unroll") for (int m = 0; m < 4; ++m) _Pragma("unroll") for (int n = 0; n < 2; ++n) _Pragma("unroll") for (int k = 0; k < 2; ++k) \
;             acc[ai][bj][m][n] = MFMA16(At_[m][k], Bt_[n][k], acc[ai][bj][m][n]); \
;         __builtin_amdgcn_s_setprio(0); } while (0)
; #define WAIT_V(n) asm volatile("s_waitcnt vmcnt(" #n ")" ::: "memory")
; #define BAR __builtin_amdgcn_s_barrier()
; #define STAGE(P, BASE, br, kt) do { const int sg_ = (kt) >> 3; const bf16_t* g_ = (sg_ == 0 ? BASE##0 : sg_ == 1 ? BASE##1 : BASE##2) + (size_t)(br) * K + (size_t)((kt) & 7) * 64; \
;         _Pragma("unroll") for (int i_ = 0; i_ < 2; ++i_) \
;             __builtin_amdgcn_global_load_lds((const unsigned*)(g_ + gofs[i_]), (lds_ptr_t)((P) + wb + i_ * 8192), 16, 0, 0); } while (0)
; #define BAR __builtin_amdgcn_s_barrier()
; template <class Hook>
; DI void gemm8_cat3(f32x4 (&acc)[2][2][4][2], const bf16_t* R0, const bf16_t* R1, const bf16_t* R2, const bf16_t* C0, const bf16_t* C1, const bf16_t* C2, char* shm, Hook hook) {
;     ...
;         STAGE(SB(1, 1), C, 128, tt + 3);
;         WAIT_V(6); BAR; MMA(1, 1, At, B1); BAR;
;     }
;     hook(0);
; DI void merge_scale(const Params& P, int tile, int seg, f32x4 (&acc)[2][2][4][2]) {
;     ...
;     for (int g8 = 0; g8 < 8; ++g8) {
;         const int ai = g8 >> 2, bj = (g8 >> 1) & 1, nn = g8 & 1;
;         const u32x4 ga = *gate_slot(P, tile, seg, g8), gb = *gate_slot(P, tile, seg + 1, g8);
; #pragma unroll
;         for (int e = 0; e < 8; ++e) {
;             const float rl = (float)((ga[e >> 2] >> (8 * (e & 3))) & 255u) * frcp((float)((gb[e >> 2] >> (8 * (e & 3))) & 255u));
;             const float rh = (float)((ga[2 + (e >> 2)] >> (8 * (e & 3))) & 255u) * frcp((float)((gb[2 + (e >> 2)] >> (8 * (e & 3))) & 255u));
;             acc[ai][bj][e >> 2][nn][e & 3] *= rl;
;             acc[ai][bj][2 + (e >> 2)][nn][e & 3] *= rh;
;         }
;         __builtin_amdgcn_sched_barrier(0);
;     }
	ds_read_b128 v[204:207], v157 offset:49152
	ds_read_b128 v[208:211], v157 offset:50176
	ds_read_b128 v[212:215], v156 offset:49152
	ds_read_b128 v[216:219], v156 offset:50176
	ds_read_b128 v[220:223], v155 offset:49152
	ds_read_b128 v[224:227], v155 offset:50176
	ds_read_b128 v[228:231], v154 offset:49152
	ds_read_b128 v[232:235], v154 offset:50176
	global_load_lds_dwordx4 v[172:173], off
	v_lshl_add_u64 v[172:173], s[20:21], 0, v[136:137]
	s_mov_b32 m0, s6
	s_nop 0
	global_load_lds_dwordx4 v[172:173], off
	s_barrier
	s_waitcnt lgkmcnt(0)
	s_setprio 1
	s_waitcnt lgkmcnt(0)
	v_mfma_f32_16x16x32_bf16 v[106:109], v[204:207], v[150:153], v[106:109]
	v_mfma_f32_16x16x32_bf16 v[122:125], v[204:207], v[196:199], v[122:125]
	v_mfma_f32_16x16x32_bf16 v[102:105], v[212:215], v[150:153], v[102:105]
	v_mfma_f32_16x16x32_bf16 v[118:121], v[212:215], v[196:199], v[118:121]
	v_mfma_f32_16x16x32_bf16 v[98:101], v[220:223], v[150:153], v[98:101]
	v_mfma_f32_16x16x32_bf16 v[114:117], v[220:223], v[196:199], v[114:117]
	v_mfma_f32_16x16x32_bf16 v[94:97], v[228:231], v[150:153], v[94:97]
	v_mfma_f32_16x16x32_bf16 v[110:113], v[228:231], v[196:199], v[110:113]
	v_mfma_f32_16x16x32_bf16 v[106:109], v[208:211], v[192:195], v[106:109]
	v_mfma_f32_16x16x32_bf16 v[122:125], v[208:211], v[200:203], v[122:125]
	v_mfma_f32_16x16x32_bf16 v[102:105], v[216:219], v[192:195], v[102:105]
	v_mfma_f32_16x16x32_bf16 v[118:121], v[216:219], v[200:203], v[118:121]
	v_mfma_f32_16x16x32_bf16 v[98:101], v[224:227], v[192:195], v[98:101]
	v_mfma_f32_16x16x32_bf16 v[114:117], v[224:227], v[200:203], v[114:117]
	v_mfma_f32_16x16x32_bf16 v[94:97], v[232:235], v[192:195], v[94:97]
	v_mfma_f32_16x16x32_bf16 v[110:113], v[232:235], v[200:203], v[110:113]
	s_setprio 0
	s_barrier
	s_add_u32 s16, s16, 0x20000
	s_addc_u32 s17, s17, 0
	v_readfirstlane_b32 s6, v186
	v_lshl_add_u64 v[150:151], s[16:17], 0, v[134:135]
	s_mov_b32 m0, s6
	v_readfirstlane_b32 s6, v187
	global_load_lds_dwordx4 v[150:151], off
	v_lshl_add_u64 v[150:151], s[16:17], 0, v[136:137]
	s_mov_b32 m0, s6
	s_nop 0
	global_load_lds_dwordx4 v[150:151], off
	s_waitcnt vmcnt(6)
	s_barrier
	s_setprio 1
	v_mfma_f32_16x16x32_bf16 v[126:129], v[204:207], v[236:239], v[126:129]
	v_mfma_f32_16x16x32_bf16 v[14:17], v[204:207], v[244:247], v[14:17]
	v_mfma_f32_16x16x32_bf16 v[34:37], v[212:215], v[236:239], v[34:37]
	v_mfma_f32_16x16x32_bf16 v[6:9], v[212:215], v[244:247], v[6:9]
	v_mfma_f32_16x16x32_bf16 v[38:41], v[220:223], v[236:239], v[38:41]
	v_mfma_f32_16x16x32_bf16 v[10:13], v[220:223], v[244:247], v[10:13]
	v_mfma_f32_16x16x32_bf16 v[22:25], v[228:231], v[236:239], v[22:25]
	v_mfma_f32_16x16x32_bf16 v[2:5], v[228:231], v[244:247], v[2:5]
	v_mfma_f32_16x16x32_bf16 v[126:129], v[208:211], v[240:243], v[126:129]
	v_mfma_f32_16x16x32_bf16 v[14:17], v[208:211], v[248:251], v[14:17]
	v_mfma_f32_16x16x32_bf16 v[34:37], v[216:219], v[240:243], v[34:37]
	v_mfma_f32_16x16x32_bf16 v[6:9], v[216:219], v[248:251], v[6:9]
	v_mfma_f32_16x16x32_bf16 v[38:41], v[224:227], v[240:243], v[38:41]
	v_mfma_f32_16x16x32_bf16 v[10:13], v[224:227], v[248:251], v[10:13]
	v_mfma_f32_16x16x32_bf16 v[22:25], v[232:235], v[240:243], v[22:25]
	v_mfma_f32_16x16x32_bf16 v[2:5], v[232:235], v[248:251], v[2:5]
	s_setprio 0
	s_addk_i32 s2, 0x80
	v_lshl_add_u64 v[130:131], v[130:131], 0, s[90:91]
	v_lshl_add_u64 v[132:133], v[132:133], 0, s[90:91]
	s_mov_b32 s6, s7
	s_barrier
	s_cbranch_vccnz .LBB0_56
	v_readlane_b32 s2, v255, 38
	s_add_u32 s26, s2, s12
	v_readlane_b32 s2, v255, 39
	s_addc_u32 s2, s2, s13
	v_readlane_b32 s6, v253, 42
	s_add_u32 s3, s6, s3
	v_readlane_b32 s6, v253, 43
	s_addc_u32 s34, s6, 0
	s_ashr_i32 s59, s58, 31
	s_lshl_b64 s[6:7], s[58:59], 16
	s_add_u32 s10, s6, 0x10000
	s_addc_u32 s11, s7, 0
	s_add_u32 s8, s74, s6
	v_mov_b32_e32 v130, v162
	s_addc_u32 s9, s75, s7
	s_add_u32 s56, s74, s10
	v_ashrrev_i32_e32 v131, 31, v130
	v_lshl_add_u64 v[130:131], v[130:131], 4, s[8:9]
	v_mov_b32_e32 v150, v162
	global_load_dwordx4 v[130:133], v[130:131], off
	s_addc_u32 s57, s75, s11
	v_ashrrev_i32_e32 v151, 31, v150
	v_lshl_add_u64 v[150:151], v[150:151], 4, s[56:57]
	global_load_dwordx4 v[192:195], v[150:151], off
	s_waitcnt vmcnt(1)
	v_cvt_f32_ubyte3_e32 v199, v130
	v_cvt_f32_ubyte2_e32 v198, v130
	v_cvt_f32_ubyte1_e32 v201, v130
	v_cvt_f32_ubyte0_e32 v200, v130
	s_waitcnt vmcnt(0)
; DI float frcp(float x) { return __builtin_amdgcn_rcpf(x); }
; DI u32x4* gate_slot(const Params& P, int tile, int j, int g8) { return (u32x4*)slotp(P, SL_SK) + ((size_t)(tile * 3 + j) * 8 + g8) * 512 + tid(); }
; DI void merge_scale(const Params& P, int tile, int seg, f32x4 (&acc)[2][2][4][2]) {
;     ...
;     for (int g8 = 0; g8 < 8; ++g8) {
;         const int ai = g8 >> 2, bj = (g8 >> 1) & 1, nn = g8 & 1;
;         const u32x4 ga = *gate_slot(P, tile, seg, g8), gb = *gate_slot(P, tile, seg + 1, g8);
; #pragma unroll
;         for (int e = 0; e < 8; ++e) {
;             const float rl = (float)((ga[e >> 2] >> (8 * (e & 3))) & 255u) * frcp((float)((gb[e >> 2] >> (8 * (e & 3))) & 255u));
;             const float rh = (float)((ga[2 + (e >> 2)] >> (8 * (e & 3))) & 255u) * frcp((float)((gb[2 + (e >> 2)] >> (8 * (e & 3))) & 255u));
;             acc[ai][bj][e >> 2][nn][e & 3] *= rl;
;             acc[ai][bj][2 + (e >> 2)][nn][e & 3] *= rh;
;         }
;         __builtin_amdgcn_sched_barrier(0);
;     }
	v_cvt_f32_ubyte0_e32 v151, v194
	v_cvt_f32_ubyte2_e32 v173, v194
	v_cvt_f32_ubyte0_e32 v150, v192
	v_rcp_iflag_f32_e32 v152, v151
	v_cvt_f32_ubyte1_e32 v151, v192
	v_cvt_f32_ubyte2_e32 v172, v192
	v_rcp_iflag_f32_e32 v196, v173
	v_cvt_f32_ubyte3_e32 v173, v192
	v_rcp_iflag_f32_e32 v150, v150
	v_rcp_iflag_f32_e32 v151, v151
	v_rcp_iflag_f32_e32 v172, v172
	v_rcp_iflag_f32_e32 v173, v173
	v_cvt_f32_ubyte1_e32 v153, v194
	v_cvt_f32_ubyte3_e32 v192, v194
	v_rcp_iflag_f32_e32 v153, v153
	v_rcp_iflag_f32_e32 v197, v192
	v_pk_mul_f32 v[150:151], v[150:151], v[200:201]
	v_pk_mul_f32 v[172:173], v[172:173], v[198:199]
	v_pk_mul_f32 v[18:19], v[18:19], v[150:151]
	v_pk_mul_f32 v[20:21], v[20:21], v[172:173]
	v_cvt_f32_ubyte3_e32 v151, v132
	v_cvt_f32_ubyte2_e32 v150, v132
	v_cvt_f32_ubyte1_e32 v173, v132
	v_cvt_f32_ubyte0_e32 v172, v132
	v_cvt_f32_ubyte0_e32 v130, v193
	v_pk_mul_f32 v[152:153], v[152:153], v[172:173]
	v_pk_mul_f32 v[150:151], v[196:197], v[150:151]
	v_rcp_iflag_f32_e32 v172, v130
	v_cvt_f32_ubyte0_e32 v130, v195
	v_pk_mul_f32 v[28:29], v[28:29], v[150:151]
	v_rcp_iflag_f32_e32 v150, v130
	v_cvt_f32_ubyte1_e32 v130, v193
	v_rcp_iflag_f32_e32 v173, v130
	v_cvt_f32_ubyte1_e32 v130, v195
	v_rcp_iflag_f32_e32 v151, v130
	v_cvt_f32_ubyte2_e32 v130, v193
	v_rcp_iflag_f32_e32 v192, v130
	v_cvt_f32_ubyte2_e32 v130, v195
	v_pk_mul_f32 v[26:27], v[26:27], v[152:153]
	v_rcp_iflag_f32_e32 v152, v130
	v_cvt_f32_ubyte3_e32 v130, v193
	v_rcp_iflag_f32_e32 v193, v130
	v_cvt_f32_ubyte3_e32 v130, v195
	v_rcp_iflag_f32_e32 v153, v130
	v_cvt_f32_ubyte3_e32 v195, v131
	v_cvt_f32_ubyte2_e32 v194, v131
	v_cvt_f32_ubyte1_e32 v197, v131
	v_cvt_f32_ubyte0_e32 v196, v131
	v_pk_mul_f32 v[130:131], v[172:173], v[196:197]
	v_pk_mul_f32 v[172:173], v[192:193], v[194:195]
	v_pk_mul_f32 v[30:31], v[30:31], v[130:131]
	v_pk_mul_f32 v[32:33], v[32:33], v[172:173]
	v_cvt_f32_ubyte3_e32 v131, v133
	v_cvt_f32_ubyte2_e32 v130, v133
	v_cvt_f32_ubyte1_e32 v173, v133
	v_cvt_f32_ubyte0_e32 v172, v133
	v_pk_mul_f32 v[132:133], v[150:151], v[172:173]
	v_pk_mul_f32 v[130:131], v[152:153], v[130:131]
	v_pk_mul_f32 v[42:43], v[42:43], v[132:133]
	v_pk_mul_f32 v[44:45], v[44:45], v[130:131]
	s_add_u32 s8, s62, s6
	v_mov_b32_e32 v130, v162
	s_addc_u32 s9, s63, s7
	s_mov_b32 s6, 0x13802000
	v_ashrrev_i32_e32 v131, 31, v130
	v_lshl_add_u64 v[130:131], v[130:131], 4, s[8:9]
	s_add_u32 s22, s62, s10
	v_add_co_u32_e32 v130, vcc, s6, v130
	s_addc_u32 s23, s63, s11
	s_nop 0
	v_addc_co_u32_e32 v131, vcc, 0, v131, vcc
	s_add_u32 s54, s22, 0x13802000
	v_mov_b32_e32 v150, v162
	global_load_dwordx4 v[130:133], v[130:131], off
	s_addc_u32 s55, s23, 0
	v_ashrrev_i32_e32 v151, 31, v150
	v_lshl_add_u64 v[150:151], v[150:151], 4, s[54:55]
	global_load_dwordx4 v[192:195], v[150:151], off
	s_waitcnt vmcnt(1)
	v_cvt_f32_ubyte3_e32 v199, v130
	v_cvt_f32_ubyte2_e32 v198, v130
	v_cvt_f32_ubyte1_e32 v201, v130
	v_cvt_f32_ubyte0_e32 v200, v130
	s_waitcnt vmcnt(0)
	v_cvt_f32_ubyte0_e32 v151, v194
	v_cvt_f32_ubyte2_e32 v173, v194
	v_cvt_f32_ubyte0_e32 v150, v192
	v_rcp_iflag_f32_e32 v152, v151
	v_cvt_f32_ubyte1_e32 v151, v192
	v_cvt_f32_ubyte2_e32 v172, v192
	v_rcp_iflag_f32_e32 v196, v173
	v_cvt_f32_ubyte3_e32 v173, v192
	v_rcp_iflag_f32_e32 v150, v150
	v_rcp_iflag_f32_e32 v151, v151
	v_rcp_iflag_f32_e32 v172, v172
	v_rcp_iflag_f32_e32 v173, v173
	v_cvt_f32_ubyte1_e32 v153, v194
	v_cvt_f32_ubyte3_e32 v192, v194
	v_rcp_iflag_f32_e32 v153, v153
	v_rcp_iflag_f32_e32 v197, v192
	v_pk_mul_f32 v[150:151], v[150:151], v[200:201]
	v_pk_mul_f32 v[172:173], v[172:173], v[198:199]
	v_pk_mul_f32 v[58:59], v[58:59], v[150:151]
	v_pk_mul_f32 v[60:61], v[60:61], v[172:173]
	v_cvt_f32_ubyte3_e32 v151, v132
	v_cvt_f32_ubyte2_e32 v150, v132
	v_cvt_f32_ubyte1_e32 v173, v132
	v_cvt_f32_ubyte0_e32 v172, v132
	v_cvt_f32_ubyte0_e32 v130, v193
	v_pk_mul_f32 v[152:153], v[152:153], v[172:173]
	v_pk_mul_f32 v[150:151], v[196:197], v[150:151]
	v_rcp_iflag_f32_e32 v172, v130
	v_cvt_f32_ubyte0_e32 v130, v195
	v_pk_mul_f32 v[52:53], v[52:53], v[150:151]
	v_rcp_iflag_f32_e32 v150, v130
	v_cvt_f32_ubyte1_e32 v130, v193
	v_rcp_iflag_f32_e32 v173, v130
	v_cvt_f32_ubyte1_e32 v130, v195
	v_rcp_iflag_f32_e32 v151, v130
	v_cvt_f32_ubyte2_e32 v130, v193
	v_rcp_iflag_f32_e32 v192, v130
	v_cvt_f32_ubyte2_e32 v130, v195
	v_pk_mul_f32 v[50:51], v[50:51], v[152:153]
	v_rcp_iflag_f32_e32 v152, v130
	v_cvt_f32_ubyte3_e32 v130, v193
	v_rcp_iflag_f32_e32 v193, v130
	v_cvt_f32_ubyte3_e32 v130, v195
	v_rcp_iflag_f32_e32 v153, v130
	v_cvt_f32_ubyte3_e32 v195, v131
	v_cvt_f32_ubyte2_e32 v194, v131
	v_cvt_f32_ubyte1_e32 v197, v131
	v_cvt_f32_ubyte0_e32 v196, v131
	v_pk_mul_f32 v[130:131], v[172:173], v[196:197]
	v_pk_mul_f32 v[172:173], v[192:193], v[194:195]
	v_pk_mul_f32 v[54:55], v[54:55], v[130:131]
	v_pk_mul_f32 v[56:57], v[56:57], v[172:173]
	v_cvt_f32_ubyte3_e32 v131, v133
	v_cvt_f32_ubyte2_e32 v130, v133
	v_cvt_f32_ubyte1_e32 v173, v133
	v_cvt_f32_ubyte0_e32 v172, v133
	v_pk_mul_f32 v[132:133], v[150:151], v[172:173]
	v_pk_mul_f32 v[130:131], v[152:153], v[130:131]
	v_pk_mul_f32 v[46:47], v[46:47], v[132:133]
	v_pk_mul_f32 v[48:49], v[48:49], v[130:131]
	v_mov_b32_e32 v130, v162
	s_mov_b32 s6, 0x13804000
	v_ashrrev_i32_e32 v131, 31, v130
	v_lshl_add_u64 v[130:131], v[130:131], 4, s[8:9]
	v_add_co_u32_e32 v130, vcc, s6, v130
	s_add_u32 s6, s22, 0x13804000
	s_nop 0
	v_addc_co_u32_e32 v131, vcc, 0, v131, vcc
	v_mov_b32_e32 v150, v162
	global_load_dwordx4 v[130:133], v[130:131], off
	s_addc_u32 s7, s23, 0
	v_ashrrev_i32_e32 v151, 31, v150
	v_lshl_add_u64 v[150:151], v[150:151], 4, s[6:7]
	global_load_dwordx4 v[192:195], v[150:151], off
	s_waitcnt vmcnt(1)
; DI float frcp(float x) { return __builtin_amdgcn_rcpf(x); }
; DI u32x4* gate_slot(const Params& P, int tile, int j, int g8) { return (u32x4*)slotp(P, SL_SK) + ((size_t)(tile * 3 + j) * 8 + g8) * 512 + tid(); }
; DI void merge_scale(const Params& P, int tile, int seg, f32x4 (&acc)[2][2][4][2]) {
;     ...
;     for (int g8 = 0; g8 < 8; ++g8) {
;         const int ai = g8 >> 2, bj = (g8 >> 1) & 1, nn = g8 & 1;
;         const u32x4 ga = *gate_slot(P, tile, seg, g8), gb = *gate_slot(P, tile, seg + 1, g8);
; #pragma unroll
;         for (int e = 0; e < 8; ++e) {
;             const float rl = (float)((ga[e >> 2] >> (8 * (e & 3))) & 255u) * frcp((float)((gb[e >> 2] >> (8 * (e & 3))) & 255u));
;             const float rh = (float)((ga[2 + (e >> 2)] >> (8 * (e & 3))) & 255u) * frcp((float)((gb[2 + (e >> 2)] >> (8 * (e & 3))) & 255u));
;             acc[ai][bj][e >> 2][nn][e & 3] *= rl;
;             acc[ai][bj][2 + (e >> 2)][nn][e & 3] *= rh;
;         }
;         __builtin_amdgcn_sched_barrier(0);
;     }
	v_cvt_f32_ubyte3_e32 v199, v130
	v_cvt_f32_ubyte2_e32 v198, v130
	v_cvt_f32_ubyte1_e32 v201, v130
	v_cvt_f32_ubyte0_e32 v200, v130
	s_waitcnt vmcnt(0)
	v_cvt_f32_ubyte0_e32 v151, v194
	v_cvt_f32_ubyte2_e32 v173, v194
	v_cvt_f32_ubyte0_e32 v150, v192
	v_rcp_iflag_f32_e32 v152, v151
	v_cvt_f32_ubyte1_e32 v151, v192
	v_cvt_f32_ubyte2_e32 v172, v192
	v_rcp_iflag_f32_e32 v196, v173
	v_cvt_f32_ubyte3_e32 v173, v192
	v_rcp_iflag_f32_e32 v150, v150
	v_rcp_iflag_f32_e32 v151, v151
	v_rcp_iflag_f32_e32 v172, v172
	v_rcp_iflag_f32_e32 v173, v173
	v_cvt_f32_ubyte1_e32 v153, v194
	v_cvt_f32_ubyte3_e32 v192, v194
	v_rcp_iflag_f32_e32 v153, v153
	v_rcp_iflag_f32_e32 v197, v192
	v_pk_mul_f32 v[150:151], v[150:151], v[200:201]
	v_pk_mul_f32 v[172:173], v[172:173], v[198:199]
	v_pk_mul_f32 v[74:75], v[74:75], v[150:151]
	v_pk_mul_f32 v[76:77], v[76:77], v[172:173]
	v_cvt_f32_ubyte3_e32 v151, v132
	v_cvt_f32_ubyte2_e32 v150, v132
	v_cvt_f32_ubyte1_e32 v173, v132
	v_cvt_f32_ubyte0_e32 v172, v132
	v_cvt_f32_ubyte0_e32 v130, v193
	v_pk_mul_f32 v[152:153], v[152:153], v[172:173]
	v_pk_mul_f32 v[150:151], v[196:197], v[150:151]
	v_rcp_iflag_f32_e32 v172, v130
	v_cvt_f32_ubyte0_e32 v130, v195
	v_pk_mul_f32 v[68:69], v[68:69], v[150:151]
	v_rcp_iflag_f32_e32 v150, v130
	v_cvt_f32_ubyte1_e32 v130, v193
	v_rcp_iflag_f32_e32 v173, v130
	v_cvt_f32_ubyte1_e32 v130, v195
	v_rcp_iflag_f32_e32 v151, v130
	v_cvt_f32_ubyte2_e32 v130, v193
	v_rcp_iflag_f32_e32 v192, v130
	v_cvt_f32_ubyte2_e32 v130, v195
	v_pk_mul_f32 v[66:67], v[66:67], v[152:153]
	v_rcp_iflag_f32_e32 v152, v130
	v_cvt_f32_ubyte3_e32 v130, v193
	v_rcp_iflag_f32_e32 v193, v130
	v_cvt_f32_ubyte3_e32 v130, v195
	v_rcp_iflag_f32_e32 v153, v130
	v_cvt_f32_ubyte3_e32 v195, v131
	v_cvt_f32_ubyte2_e32 v194, v131
	v_cvt_f32_ubyte1_e32 v197, v131
	v_cvt_f32_ubyte0_e32 v196, v131
	v_pk_mul_f32 v[130:131], v[172:173], v[196:197]
	v_pk_mul_f32 v[172:173], v[192:193], v[194:195]
	v_pk_mul_f32 v[70:71], v[70:71], v[130:131]
	v_pk_mul_f32 v[72:73], v[72:73], v[172:173]
	v_cvt_f32_ubyte3_e32 v131, v133
	v_cvt_f32_ubyte2_e32 v130, v133
	v_cvt_f32_ubyte1_e32 v173, v133
	v_cvt_f32_ubyte0_e32 v172, v133
	v_pk_mul_f32 v[132:133], v[150:151], v[172:173]
	v_pk_mul_f32 v[130:131], v[152:153], v[130:131]
	v_pk_mul_f32 v[62:63], v[62:63], v[132:133]
	v_pk_mul_f32 v[64:65], v[64:65], v[130:131]
	v_mov_b32_e32 v130, v162
	s_mov_b32 s10, 0x13806000
	v_ashrrev_i32_e32 v131, 31, v130
	v_lshl_add_u64 v[130:131], v[130:131], 4, s[8:9]
	v_add_co_u32_e32 v130, vcc, s10, v130
	s_add_u32 s10, s22, 0x13806000
	s_nop 0
	v_addc_co_u32_e32 v131, vcc, 0, v131, vcc
	v_mov_b32_e32 v150, v162
	global_load_dwordx4 v[130:133], v[130:131], off
	s_addc_u32 s11, s23, 0
	v_ashrrev_i32_e32 v151, 31, v150
	v_lshl_add_u64 v[150:151], v[150:151], 4, s[10:11]
	global_load_dwordx4 v[192:195], v[150:151], off
	s_waitcnt vmcnt(1)
	v_cvt_f32_ubyte3_e32 v199, v130
	v_cvt_f32_ubyte2_e32 v198, v130
	v_cvt_f32_ubyte1_e32 v201, v130
	v_cvt_f32_ubyte0_e32 v200, v130
	s_waitcnt vmcnt(0)
	v_cvt_f32_ubyte0_e32 v151, v194
	v_cvt_f32_ubyte2_e32 v173, v194
	v_cvt_f32_ubyte0_e32 v150, v192
	v_rcp_iflag_f32_e32 v152, v151
	v_cvt_f32_ubyte1_e32 v151, v192
	v_cvt_f32_ubyte2_e32 v172, v192
	v_rcp_iflag_f32_e32 v196, v173
	v_cvt_f32_ubyte3_e32 v173, v192
	v_rcp_iflag_f32_e32 v150, v150
	v_rcp_iflag_f32_e32 v151, v151
	v_rcp_iflag_f32_e32 v172, v172
	v_rcp_iflag_f32_e32 v173, v173
	v_cvt_f32_ubyte1_e32 v153, v194
	v_cvt_f32_ubyte3_e32 v192, v194
	v_rcp_iflag_f32_e32 v153, v153
	v_rcp_iflag_f32_e32 v197, v192
	v_pk_mul_f32 v[150:151], v[150:151], v[200:201]
	v_pk_mul_f32 v[172:173], v[172:173], v[198:199]
	v_pk_mul_f32 v[90:91], v[90:91], v[150:151]
	v_pk_mul_f32 v[92:93], v[92:93], v[172:173]
	v_cvt_f32_ubyte3_e32 v151, v132
	v_cvt_f32_ubyte2_e32 v150, v132
	v_cvt_f32_ubyte1_e32 v173, v132
	v_cvt_f32_ubyte0_e32 v172, v132
	v_cvt_f32_ubyte0_e32 v130, v193
	v_pk_mul_f32 v[152:153], v[152:153], v[172:173]
	v_pk_mul_f32 v[150:151], v[196:197], v[150:151]
	v_rcp_iflag_f32_e32 v172, v130
	v_cvt_f32_ubyte0_e32 v130, v195
	v_pk_mul_f32 v[84:85], v[84:85], v[150:151]
	v_rcp_iflag_f32_e32 v150, v130
	v_cvt_f32_ubyte1_e32 v130, v193
	v_rcp_iflag_f32_e32 v173, v130
	v_cvt_f32_ubyte1_e32 v130, v195
	v_rcp_iflag_f32_e32 v151, v130
	v_cvt_f32_ubyte2_e32 v130, v193
	v_rcp_iflag_f32_e32 v192, v130
	v_cvt_f32_ubyte2_e32 v130, v195
	v_pk_mul_f32 v[82:83], v[82:83], v[152:153]
	v_rcp_iflag_f32_e32 v152, v130
	v_cvt_f32_ubyte3_e32 v130, v193
	v_rcp_iflag_f32_e32 v193, v130
	v_cvt_f32_ubyte3_e32 v130, v195
	v_rcp_iflag_f32_e32 v153, v130
	v_cvt_f32_ubyte3_e32 v195, v131
	v_cvt_f32_ubyte2_e32 v194, v131
	v_cvt_f32_ubyte1_e32 v197, v131
	v_cvt_f32_ubyte0_e32 v196, v131
	v_pk_mul_f32 v[130:131], v[172:173], v[196:197]
	v_pk_mul_f32 v[172:173], v[192:193], v[194:195]
	v_pk_mul_f32 v[86:87], v[86:87], v[130:131]
	v_pk_mul_f32 v[88:89], v[88:89], v[172:173]
	v_cvt_f32_ubyte3_e32 v131, v133
	v_cvt_f32_ubyte2_e32 v130, v133
	v_cvt_f32_ubyte1_e32 v173, v133
	v_cvt_f32_ubyte0_e32 v172, v133
	v_pk_mul_f32 v[132:133], v[150:151], v[172:173]
	v_pk_mul_f32 v[130:131], v[152:153], v[130:131]
	v_pk_mul_f32 v[78:79], v[78:79], v[132:133]
	v_pk_mul_f32 v[80:81], v[80:81], v[130:131]
	v_mov_b32_e32 v130, v162
	s_mov_b32 s12, 0x13808000
	v_ashrrev_i32_e32 v131, 31, v130
	v_lshl_add_u64 v[130:131], v[130:131], 4, s[8:9]
	v_add_co_u32_e32 v130, vcc, s12, v130
	s_add_u32 s12, s22, 0x13808000
	s_nop 0
	v_addc_co_u32_e32 v131, vcc, 0, v131, vcc
	v_mov_b32_e32 v150, v162
	global_load_dwordx4 v[130:133], v[130:131], off
	s_addc_u32 s13, s23, 0
	v_ashrrev_i32_e32 v151, 31, v150
	v_lshl_add_u64 v[150:151], v[150:151], 4, s[12:13]
	global_load_dwordx4 v[192:195], v[150:151], off
	s_waitcnt vmcnt(1)
; DI float frcp(float x) { return __builtin_amdgcn_rcpf(x); }
; DI u32x4* gate_slot(const Params& P, int tile, int j, int g8) { return (u32x4*)slotp(P, SL_SK) + ((size_t)(tile * 3 + j) * 8 + g8) * 512 + tid(); }
; DI void merge_scale(const Params& P, int tile, int seg, f32x4 (&acc)[2][2][4][2]) {
;     ...
;     for (int g8 = 0; g8 < 8; ++g8) {
;         const int ai = g8 >> 2, bj = (g8 >> 1) & 1, nn = g8 & 1;
;         const u32x4 ga = *gate_slot(P, tile, seg, g8), gb = *gate_slot(P, tile, seg + 1, g8);
; #pragma unroll
;         for (int e = 0; e < 8; ++e) {
;             const float rl = (float)((ga[e >> 2] >> (8 * (e & 3))) & 255u) * frcp((float)((gb[e >> 2] >> (8 * (e & 3))) & 255u));
;             const float rh = (float)((ga[2 + (e >> 2)] >> (8 * (e & 3))) & 255u) * frcp((float)((gb[2 + (e >> 2)] >> (8 * (e & 3))) & 255u));
;             acc[ai][bj][e >> 2][nn][e & 3] *= rl;
;             acc[ai][bj][2 + (e >> 2)][nn][e & 3] *= rh;
;         }
;         __builtin_amdgcn_sched_barrier(0);
;     }
	v_cvt_f32_ubyte3_e32 v199, v130
	v_cvt_f32_ubyte2_e32 v198, v130
	v_cvt_f32_ubyte1_e32 v201, v130
	v_cvt_f32_ubyte0_e32 v200, v130
	s_waitcnt vmcnt(0)
	v_cvt_f32_ubyte0_e32 v151, v194
	v_cvt_f32_ubyte2_e32 v173, v194
	v_cvt_f32_ubyte0_e32 v150, v192
	v_rcp_iflag_f32_e32 v152, v151
	v_cvt_f32_ubyte1_e32 v151, v192
	v_cvt_f32_ubyte2_e32 v172, v192
	v_rcp_iflag_f32_e32 v196, v173
	v_cvt_f32_ubyte3_e32 v173, v192
	v_rcp_iflag_f32_e32 v150, v150
	v_rcp_iflag_f32_e32 v151, v151
	v_rcp_iflag_f32_e32 v172, v172
	v_rcp_iflag_f32_e32 v173, v173
	v_cvt_f32_ubyte1_e32 v153, v194
	v_cvt_f32_ubyte3_e32 v192, v194
	v_rcp_iflag_f32_e32 v153, v153
	v_rcp_iflag_f32_e32 v197, v192
	v_pk_mul_f32 v[150:151], v[150:151], v[200:201]
	v_pk_mul_f32 v[172:173], v[172:173], v[198:199]
	v_pk_mul_f32 v[106:107], v[106:107], v[150:151]
	v_pk_mul_f32 v[108:109], v[108:109], v[172:173]
	v_cvt_f32_ubyte3_e32 v151, v132
	v_cvt_f32_ubyte2_e32 v150, v132
	v_cvt_f32_ubyte1_e32 v173, v132
	v_cvt_f32_ubyte0_e32 v172, v132
	v_cvt_f32_ubyte0_e32 v130, v193
	v_pk_mul_f32 v[152:153], v[152:153], v[172:173]
	v_pk_mul_f32 v[150:151], v[196:197], v[150:151]
	v_rcp_iflag_f32_e32 v172, v130
	v_cvt_f32_ubyte0_e32 v130, v195
	v_pk_mul_f32 v[100:101], v[100:101], v[150:151]
	v_rcp_iflag_f32_e32 v150, v130
	v_cvt_f32_ubyte1_e32 v130, v193
	v_rcp_iflag_f32_e32 v173, v130
	v_cvt_f32_ubyte1_e32 v130, v195
	v_rcp_iflag_f32_e32 v151, v130
	v_cvt_f32_ubyte2_e32 v130, v193
	v_rcp_iflag_f32_e32 v192, v130
	v_cvt_f32_ubyte2_e32 v130, v195
	v_pk_mul_f32 v[98:99], v[98:99], v[152:153]
	v_rcp_iflag_f32_e32 v152, v130
	v_cvt_f32_ubyte3_e32 v130, v193
	v_rcp_iflag_f32_e32 v193, v130
	v_cvt_f32_ubyte3_e32 v130, v195
	v_rcp_iflag_f32_e32 v153, v130
	v_cvt_f32_ubyte3_e32 v195, v131
	v_cvt_f32_ubyte2_e32 v194, v131
	v_cvt_f32_ubyte1_e32 v197, v131
	v_cvt_f32_ubyte0_e32 v196, v131
	v_pk_mul_f32 v[130:131], v[172:173], v[196:197]
	v_pk_mul_f32 v[172:173], v[192:193], v[194:195]
	v_pk_mul_f32 v[102:103], v[102:103], v[130:131]
	v_pk_mul_f32 v[104:105], v[104:105], v[172:173]
	v_cvt_f32_ubyte3_e32 v131, v133
	v_cvt_f32_ubyte2_e32 v130, v133
	v_cvt_f32_ubyte1_e32 v173, v133
	v_cvt_f32_ubyte0_e32 v172, v133
	v_pk_mul_f32 v[132:133], v[150:151], v[172:173]
	v_pk_mul_f32 v[130:131], v[152:153], v[130:131]
	v_pk_mul_f32 v[94:95], v[94:95], v[132:133]
	v_pk_mul_f32 v[96:97], v[96:97], v[130:131]
	v_mov_b32_e32 v130, v162
	s_mov_b32 s16, 0x1380a000
	v_ashrrev_i32_e32 v131, 31, v130
	v_lshl_add_u64 v[130:131], v[130:131], 4, s[8:9]
	v_add_co_u32_e32 v130, vcc, s16, v130
	s_add_u32 s16, s22, 0x1380a000
	s_nop 0
	v_addc_co_u32_e32 v131, vcc, 0, v131, vcc
	v_mov_b32_e32 v150, v162
	global_load_dwordx4 v[130:133], v[130:131], off
	s_addc_u32 s17, s23, 0
	v_ashrrev_i32_e32 v151, 31, v150
	v_lshl_add_u64 v[150:151], v[150:151], 4, s[16:17]
	global_load_dwordx4 v[192:195], v[150:151], off
	s_waitcnt vmcnt(1)
	v_cvt_f32_ubyte3_e32 v199, v130
	v_cvt_f32_ubyte2_e32 v198, v130
	v_cvt_f32_ubyte1_e32 v201, v130
	v_cvt_f32_ubyte0_e32 v200, v130
	s_waitcnt vmcnt(0)
	v_cvt_f32_ubyte0_e32 v151, v194
	v_cvt_f32_ubyte2_e32 v173, v194
	v_cvt_f32_ubyte0_e32 v150, v192
	v_rcp_iflag_f32_e32 v152, v151
	v_cvt_f32_ubyte1_e32 v151, v192
	v_cvt_f32_ubyte2_e32 v172, v192
	v_rcp_iflag_f32_e32 v196, v173
	v_cvt_f32_ubyte3_e32 v173, v192
	v_rcp_iflag_f32_e32 v150, v150
	v_rcp_iflag_f32_e32 v151, v151
	v_rcp_iflag_f32_e32 v172, v172
	v_rcp_iflag_f32_e32 v173, v173
	v_cvt_f32_ubyte1_e32 v153, v194
	v_cvt_f32_ubyte3_e32 v192, v194
	v_rcp_iflag_f32_e32 v153, v153
	v_rcp_iflag_f32_e32 v197, v192
	v_pk_mul_f32 v[150:151], v[150:151], v[200:201]
	v_pk_mul_f32 v[172:173], v[172:173], v[198:199]
	v_pk_mul_f32 v[122:123], v[122:123], v[150:151]
	v_pk_mul_f32 v[124:125], v[124:125], v[172:173]
	v_cvt_f32_ubyte3_e32 v151, v132
	v_cvt_f32_ubyte2_e32 v150, v132
	v_cvt_f32_ubyte1_e32 v173, v132
	v_cvt_f32_ubyte0_e32 v172, v132
	v_cvt_f32_ubyte0_e32 v130, v193
	v_pk_mul_f32 v[152:153], v[152:153], v[172:173]
	v_pk_mul_f32 v[150:151], v[196:197], v[150:151]
	v_rcp_iflag_f32_e32 v172, v130
	v_cvt_f32_ubyte0_e32 v130, v195
	v_pk_mul_f32 v[116:117], v[116:117], v[150:151]
	v_rcp_iflag_f32_e32 v150, v130
	v_cvt_f32_ubyte1_e32 v130, v193
	v_rcp_iflag_f32_e32 v173, v130
	v_cvt_f32_ubyte1_e32 v130, v195
	v_rcp_iflag_f32_e32 v151, v130
	v_cvt_f32_ubyte2_e32 v130, v193
	v_rcp_iflag_f32_e32 v192, v130
	v_cvt_f32_ubyte2_e32 v130, v195
	v_pk_mul_f32 v[114:115], v[114:115], v[152:153]
	v_rcp_iflag_f32_e32 v152, v130
	v_cvt_f32_ubyte3_e32 v130, v193
	v_rcp_iflag_f32_e32 v193, v130
	v_cvt_f32_ubyte3_e32 v130, v195
	v_rcp_iflag_f32_e32 v153, v130
	v_cvt_f32_ubyte3_e32 v195, v131
	v_cvt_f32_ubyte2_e32 v194, v131
	v_cvt_f32_ubyte1_e32 v197, v131
	v_cvt_f32_ubyte0_e32 v196, v131
	v_pk_mul_f32 v[130:131], v[172:173], v[196:197]
	v_pk_mul_f32 v[172:173], v[192:193], v[194:195]
	v_pk_mul_f32 v[118:119], v[118:119], v[130:131]
	v_pk_mul_f32 v[120:121], v[120:121], v[172:173]
	v_cvt_f32_ubyte3_e32 v131, v133
	v_cvt_f32_ubyte2_e32 v130, v133
	v_cvt_f32_ubyte1_e32 v173, v133
	v_cvt_f32_ubyte0_e32 v172, v133
	v_pk_mul_f32 v[132:133], v[150:151], v[172:173]
	v_pk_mul_f32 v[130:131], v[152:153], v[130:131]
	v_pk_mul_f32 v[110:111], v[110:111], v[132:133]
	v_pk_mul_f32 v[112:113], v[112:113], v[130:131]
	v_mov_b32_e32 v130, v162
	s_mov_b32 s20, 0x1380c000
	v_ashrrev_i32_e32 v131, 31, v130
	v_lshl_add_u64 v[130:131], v[130:131], 4, s[8:9]
	v_add_co_u32_e32 v130, vcc, s20, v130
	s_add_u32 s20, s22, 0x1380c000
	s_nop 0
	v_addc_co_u32_e32 v131, vcc, 0, v131, vcc
	v_mov_b32_e32 v150, v162
	global_load_dwordx4 v[130:133], v[130:131], off
	s_addc_u32 s21, s23, 0
	v_ashrrev_i32_e32 v151, 31, v150
	v_lshl_add_u64 v[150:151], v[150:151], 4, s[20:21]
	global_load_dwordx4 v[192:195], v[150:151], off
	s_waitcnt vmcnt(1)
; DI float frcp(float x) { return __builtin_amdgcn_rcpf(x); }
; #define STAGE(P, BASE, br, kt) do { const bf16_t* g_ = (BASE) + (size_t)(br) * K + (size_t)(kt) * 64; \
;         _Pragma("unroll") for (int i_ = 0; i_ < 2; ++i_) \
;             __builtin_amdgcn_global_load_lds((const unsigned*)(g_ + gofs[i_]), (lds_ptr_t)((P) + wb + i_ * 8192), 16, 0, 0); } while (0)
; #define LDA(dst, b, hh) _Pragma("unroll") for (int m = 0; m < 4; ++m) _Pragma("unroll") for (int k = 0; k < 2; ++k) \
;         dst[m][k] = *(const bf16x8*)(SA(b, hh) + lds_byte(wr * 64 + m * 16 + fr, k * 32 + fq * 8))
; #define LDB(dst, b, hh) _Pragma("unroll") for (int n = 0; n < 2; ++n) _Pragma("unroll") for (int k = 0; k < 2; ++k) \
;         dst[n][k] = *(const bf16x8*)(SB(b, hh) + lds_byte(wc * 32 + n * 16 + fr, k * 32 + fq * 8))
; #define SCHED __builtin_amdgcn_sched_barrier(0)
; #define STAGE(P, BASE, br, kt) do { const int sg_ = (kt) >> 3; const bf16_t* g_ = (sg_ == 0 ? BASE##0 : sg_ == 1 ? BASE##1 : BASE##2) + (size_t)(br) * K + (size_t)((kt) & 7) * 64; \
;         _Pragma("unroll") for (int i_ = 0; i_ < 2; ++i_) \
;             __builtin_amdgcn_global_load_lds((const unsigned*)(g_ + gofs[i_]), (lds_ptr_t)((P) + wb + i_ * 8192), 16, 0, 0); } while (0)
; template <class Hook>
; DI void gemm8_cat3(f32x4 (&acc)[2][2][4][2], const bf16_t* R0, const bf16_t* R1, const bf16_t* R2, const bf16_t* C0, const bf16_t* C1, const bf16_t* C2, char* shm, Hook hook) {
;     ...
;     for (int tt = 8; tt < 16; tt += 2) {
;         LDB(B0, 0, 0); SCHED; LDA(At, 0, 0); STAGE(SA(1, 1), R, 128, tt + 1);
; DI void merge_scale(const Params& P, int tile, int seg, f32x4 (&acc)[2][2][4][2]) {
;     ...
;     for (int g8 = 0; g8 < 8; ++g8) {
;         const int ai = g8 >> 2, bj = (g8 >> 1) & 1, nn = g8 & 1;
;         const u32x4 ga = *gate_slot(P, tile, seg, g8), gb = *gate_slot(P, tile, seg + 1, g8);
; #pragma unroll
;         for (int e = 0; e < 8; ++e) {
;             const float rl = (float)((ga[e >> 2] >> (8 * (e & 3))) & 255u) * frcp((float)((gb[e >> 2] >> (8 * (e & 3))) & 255u));
;             const float rh = (float)((ga[2 + (e >> 2)] >> (8 * (e & 3))) & 255u) * frcp((float)((gb[2 + (e >> 2)] >> (8 * (e & 3))) & 255u));
;             acc[ai][bj][e >> 2][nn][e & 3] *= rl;
;             acc[ai][bj][2 + (e >> 2)][nn][e & 3] *= rh;
;         }
;         __builtin_amdgcn_sched_barrier(0);
;     }
	v_cvt_f32_ubyte3_e32 v199, v130
	v_cvt_f32_ubyte2_e32 v198, v130
	v_cvt_f32_ubyte1_e32 v201, v130
	v_cvt_f32_ubyte0_e32 v200, v130
	s_waitcnt vmcnt(0)
	v_cvt_f32_ubyte0_e32 v151, v194
	v_cvt_f32_ubyte2_e32 v173, v194
	v_cvt_f32_ubyte0_e32 v150, v192
	v_rcp_iflag_f32_e32 v152, v151
	v_cvt_f32_ubyte1_e32 v151, v192
	v_cvt_f32_ubyte2_e32 v172, v192
	v_rcp_iflag_f32_e32 v196, v173
	v_cvt_f32_ubyte3_e32 v173, v192
	v_rcp_iflag_f32_e32 v150, v150
	v_rcp_iflag_f32_e32 v151, v151
	v_rcp_iflag_f32_e32 v172, v172
	v_rcp_iflag_f32_e32 v173, v173
	v_cvt_f32_ubyte1_e32 v153, v194
	v_cvt_f32_ubyte3_e32 v192, v194
	v_rcp_iflag_f32_e32 v153, v153
	v_rcp_iflag_f32_e32 v197, v192
	v_pk_mul_f32 v[150:151], v[150:151], v[200:201]
	v_pk_mul_f32 v[172:173], v[172:173], v[198:199]
	v_pk_mul_f32 v[126:127], v[126:127], v[150:151]
	v_pk_mul_f32 v[128:129], v[128:129], v[172:173]
	v_cvt_f32_ubyte3_e32 v151, v132
	v_cvt_f32_ubyte2_e32 v150, v132
	v_cvt_f32_ubyte1_e32 v173, v132
	v_cvt_f32_ubyte0_e32 v172, v132
	v_cvt_f32_ubyte0_e32 v130, v193
	v_pk_mul_f32 v[152:153], v[152:153], v[172:173]
	v_pk_mul_f32 v[150:151], v[196:197], v[150:151]
	v_rcp_iflag_f32_e32 v172, v130
	v_cvt_f32_ubyte0_e32 v130, v195
	v_pk_mul_f32 v[40:41], v[40:41], v[150:151]
	v_rcp_iflag_f32_e32 v150, v130
	v_cvt_f32_ubyte1_e32 v130, v193
	v_rcp_iflag_f32_e32 v173, v130
	v_cvt_f32_ubyte1_e32 v130, v195
	v_rcp_iflag_f32_e32 v151, v130
	v_cvt_f32_ubyte2_e32 v130, v193
	v_rcp_iflag_f32_e32 v192, v130
	v_cvt_f32_ubyte2_e32 v130, v195
	v_pk_mul_f32 v[38:39], v[38:39], v[152:153]
	v_rcp_iflag_f32_e32 v152, v130
	v_cvt_f32_ubyte3_e32 v130, v193
	v_rcp_iflag_f32_e32 v193, v130
	v_cvt_f32_ubyte3_e32 v130, v195
	v_rcp_iflag_f32_e32 v153, v130
	v_cvt_f32_ubyte3_e32 v195, v131
	v_cvt_f32_ubyte2_e32 v194, v131
	v_cvt_f32_ubyte1_e32 v197, v131
	v_cvt_f32_ubyte0_e32 v196, v131
	v_pk_mul_f32 v[130:131], v[172:173], v[196:197]
	v_pk_mul_f32 v[172:173], v[192:193], v[194:195]
	v_pk_mul_f32 v[34:35], v[34:35], v[130:131]
	v_pk_mul_f32 v[36:37], v[36:37], v[172:173]
	v_cvt_f32_ubyte3_e32 v131, v133
	v_cvt_f32_ubyte2_e32 v130, v133
	v_cvt_f32_ubyte1_e32 v173, v133
	v_cvt_f32_ubyte0_e32 v172, v133
	v_pk_mul_f32 v[132:133], v[150:151], v[172:173]
	v_pk_mul_f32 v[130:131], v[152:153], v[130:131]
	v_pk_mul_f32 v[22:23], v[22:23], v[132:133]
	v_pk_mul_f32 v[24:25], v[24:25], v[130:131]
	v_mov_b32_e32 v130, v162
	s_add_u32 s22, s22, 0x1380e000
	v_ashrrev_i32_e32 v131, 31, v130
	v_lshl_add_u64 v[130:131], v[130:131], 4, s[8:9]
	s_mov_b32 s8, 0x1380e000
	v_add_co_u32_e32 v130, vcc, s8, v130
	v_mov_b32_e32 v150, v162
	s_nop 0
	v_addc_co_u32_e32 v131, vcc, 0, v131, vcc
	global_load_dwordx4 v[130:133], v[130:131], off
	s_addc_u32 s23, s23, 0
	v_ashrrev_i32_e32 v151, 31, v150
	v_lshl_add_u64 v[150:151], v[150:151], 4, s[22:23]
	global_load_dwordx4 v[192:195], v[150:151], off
	s_waitcnt vmcnt(1)
	v_cvt_f32_ubyte3_e32 v199, v130
	v_cvt_f32_ubyte2_e32 v198, v130
	v_cvt_f32_ubyte1_e32 v201, v130
	v_cvt_f32_ubyte0_e32 v200, v130
	s_waitcnt vmcnt(0)
	v_cvt_f32_ubyte0_e32 v151, v194
	v_cvt_f32_ubyte2_e32 v173, v194
	v_cvt_f32_ubyte0_e32 v150, v192
	v_rcp_iflag_f32_e32 v152, v151
	v_cvt_f32_ubyte1_e32 v151, v192
	v_cvt_f32_ubyte2_e32 v172, v192
	v_rcp_iflag_f32_e32 v196, v173
	v_cvt_f32_ubyte3_e32 v173, v192
	v_rcp_iflag_f32_e32 v150, v150
	v_rcp_iflag_f32_e32 v151, v151
	v_rcp_iflag_f32_e32 v172, v172
	v_rcp_iflag_f32_e32 v173, v173
	v_cvt_f32_ubyte1_e32 v153, v194
	v_cvt_f32_ubyte3_e32 v192, v194
	v_rcp_iflag_f32_e32 v153, v153
	v_rcp_iflag_f32_e32 v197, v192
	v_pk_mul_f32 v[150:151], v[150:151], v[200:201]
	v_pk_mul_f32 v[172:173], v[172:173], v[198:199]
	v_pk_mul_f32 v[14:15], v[14:15], v[150:151]
	v_pk_mul_f32 v[16:17], v[16:17], v[172:173]
	v_cvt_f32_ubyte3_e32 v151, v132
	v_cvt_f32_ubyte2_e32 v150, v132
	v_cvt_f32_ubyte1_e32 v173, v132
	v_cvt_f32_ubyte0_e32 v172, v132
	v_cvt_f32_ubyte0_e32 v130, v193
	v_pk_mul_f32 v[152:153], v[152:153], v[172:173]
	v_pk_mul_f32 v[150:151], v[196:197], v[150:151]
	v_rcp_iflag_f32_e32 v172, v130
	v_cvt_f32_ubyte0_e32 v130, v195
	v_pk_mul_f32 v[12:13], v[12:13], v[150:151]
	v_rcp_iflag_f32_e32 v150, v130
	v_cvt_f32_ubyte1_e32 v130, v193
	v_rcp_iflag_f32_e32 v173, v130
	v_cvt_f32_ubyte1_e32 v130, v195
	v_rcp_iflag_f32_e32 v151, v130
	v_cvt_f32_ubyte2_e32 v130, v193
	v_rcp_iflag_f32_e32 v192, v130
	v_cvt_f32_ubyte2_e32 v130, v195
	v_pk_mul_f32 v[10:11], v[10:11], v[152:153]
	v_rcp_iflag_f32_e32 v152, v130
	v_cvt_f32_ubyte3_e32 v130, v193
	v_rcp_iflag_f32_e32 v193, v130
	v_cvt_f32_ubyte3_e32 v130, v195
	v_rcp_iflag_f32_e32 v153, v130
	v_cvt_f32_ubyte3_e32 v195, v131
	v_cvt_f32_ubyte2_e32 v194, v131
	v_cvt_f32_ubyte1_e32 v197, v131
	v_cvt_f32_ubyte0_e32 v196, v131
	v_pk_mul_f32 v[130:131], v[172:173], v[196:197]
	v_pk_mul_f32 v[172:173], v[192:193], v[194:195]
	v_pk_mul_f32 v[6:7], v[6:7], v[130:131]
	v_pk_mul_f32 v[8:9], v[8:9], v[172:173]
	v_cvt_f32_ubyte3_e32 v131, v133
	v_cvt_f32_ubyte2_e32 v130, v133
	v_cvt_f32_ubyte1_e32 v173, v133
	v_cvt_f32_ubyte0_e32 v172, v133
	v_pk_mul_f32 v[132:133], v[150:151], v[172:173]
	v_pk_mul_f32 v[130:131], v[152:153], v[130:131]
	v_pk_mul_f32 v[2:3], v[2:3], v[132:133]
	v_pk_mul_f32 v[4:5], v[4:5], v[130:131]
	s_mov_b64 s[8:9], s[50:51]
	v_lshl_add_u64 v[130:131], s[8:9], 0, v[146:147]
	v_lshl_add_u64 v[132:133], s[8:9], 0, v[148:149]
	s_mov_b32 s8, 6
	s_movk_i32 s9, 0x2c0
; #define STAGE(P, BASE, br, kt) do { const bf16_t* g_ = (BASE) + (size_t)(br) * K + (size_t)(kt) * 64; \
;         _Pragma("unroll") for (int i_ = 0; i_ < 2; ++i_) \
;             __builtin_amdgcn_global_load_lds((const unsigned*)(g_ + gofs[i_]), (lds_ptr_t)((P) + wb + i_ * 8192), 16, 0, 0); } while (0)
; #define LDA(dst, b, hh) _Pragma("unroll") for (int m = 0; m < 4; ++m) _Pragma("unroll") for (int k = 0; k < 2; ++k) \
;         dst[m][k] = *(const bf16x8*)(SA(b, hh) + lds_byte(wr * 64 + m * 16 + fr, k * 32 + fq * 8))
; #define LDB(dst, b, hh) _Pragma("unroll") for (int n = 0; n < 2; ++n) _Pragma("unroll") for (int k = 0; k < 2; ++k) \
;         dst[n][k] = *(const bf16x8*)(SB(b, hh) + lds_byte(wc * 32 + n * 16 + fr, k * 32 + fq * 8))
; #define MMA(ai, bj, At_, Bt_) do { __builtin_amdgcn_s_setprio(1); \
;         _Pragma("unroll") for (int m = 0; m < 4; ++m) _Pragma("unroll") for (int n = 0; n < 2; ++n) _Pragma("unroll") for (int k = 0; k < 2; ++k) \
;             acc[ai][bj][m][n] = MFMA16(At_[m][k], Bt_[n][k], acc[ai][bj][m][n]); \
;         __builtin_amdgcn_s_setprio(0); } while (0)
; #define WAIT_V(n) asm volatile("s_waitcnt vmcnt(" #n ")" ::: "memory")
; #define BAR __builtin_amdgcn_s_barrier()
; template <class Hook>
; DI void gemm8_cat3(f32x4 (&acc)[2][2][4][2], const bf16_t* R0, const bf16_t* R1, const bf16_t* R2, const bf16_t* C0, const bf16_t* C1, const bf16_t* C2, char* shm, Hook hook) {
;     ...
;     for (int tt = 8; tt < 16; tt += 2) {
;         LDB(B0, 0, 0); SCHED; LDA(At, 0, 0); STAGE(SA(1, 1), R, 128, tt + 1);
;         WAIT_L(8); BAR; WAIT_L(0); MMA(0, 0, At, B0); BAR; SCHED;
;         LDB(B1, 0, 1); STAGE(SB(0, 0), C, 0, tt + 2);
;         BAR; WAIT_L(0); MMA(0, 1, At, B1); BAR;
;         LDA(At, 0, 1); STAGE(SA(0, 0), R, 0, tt + 2);
;         BAR; WAIT_L(0); MMA(1, 0, At, B0); BAR; SCHED;
;         STAGE(SB(0, 1), C, 128, tt + 2);
;         WAIT_V(6); BAR; MMA(1, 1, At, B1); BAR;
;         LDB(B0, 1, 0); SCHED; LDA(At, 1, 0); STAGE(SA(0, 1), R, 128, tt + 2);
;         WAIT_L(8); BAR; WAIT_L(0); MMA(0, 0, At, B0); BAR; SCHED;
;         LDB(B1, 1, 1); STAGE(SB(1, 0), C, 0, tt + 3);
;         BAR; WAIT_L(0); MMA(0, 1, At, B1); BAR;
;         LDA(At, 1, 1); STAGE(SA(1, 0), R, 0, tt + 3);
;         BAR; WAIT_L(0); MMA(1, 0, At, B0); BAR; SCHED;
;         STAGE(SB(1, 1), C, 128, tt + 3);
;         WAIT_V(6); BAR; MMA(1, 1, At, B1); BAR;
;     }
.LBB0_58:
	ds_read_b128 v[146:149], v189
	ds_read_b128 v[150:153], v189 offset:1024
	ds_read_b128 v[192:195], v189 offset:2048
	ds_read_b128 v[196:199], v189 offset:3072
	v_readfirstlane_b32 s35, v190
	s_mov_b32 m0, s35
	v_readfirstlane_b32 s35, v191
	ds_read_b128 v[200:203], v157
	ds_read_b128 v[204:207], v157 offset:1024
	ds_read_b128 v[208:211], v156
	ds_read_b128 v[212:215], v156 offset:1024
	ds_read_b128 v[216:219], v155
	ds_read_b128 v[220:223], v155 offset:1024
	ds_read_b128 v[224:227], v154
	ds_read_b128 v[228:231], v154 offset:1024
	global_load_lds_dwordx4 v[130:131], off
	s_mov_b32 m0, s35
	s_nop 0
	global_load_lds_dwordx4 v[132:133], off
	s_waitcnt lgkmcnt(8)
	s_barrier
	s_waitcnt lgkmcnt(0)
	s_setprio 1
	s_waitcnt lgkmcnt(0)
	v_mfma_f32_16x16x32_bf16 v[18:21], v[200:203], v[146:149], v[18:21]
	v_mfma_f32_16x16x32_bf16 v[58:61], v[200:203], v[192:195], v[58:61]
	v_mfma_f32_16x16x32_bf16 v[30:33], v[208:211], v[146:149], v[30:33]
	v_mfma_f32_16x16x32_bf16 v[54:57], v[208:211], v[192:195], v[54:57]
	v_mfma_f32_16x16x32_bf16 v[26:29], v[216:219], v[146:149], v[26:29]
	v_mfma_f32_16x16x32_bf16 v[50:53], v[216:219], v[192:195], v[50:53]
	v_mfma_f32_16x16x32_bf16 v[42:45], v[224:227], v[146:149], v[42:45]
	v_mfma_f32_16x16x32_bf16 v[46:49], v[224:227], v[192:195], v[46:49]
	v_mfma_f32_16x16x32_bf16 v[18:21], v[204:207], v[150:153], v[18:21]
	v_mfma_f32_16x16x32_bf16 v[58:61], v[204:207], v[196:199], v[58:61]
	v_mfma_f32_16x16x32_bf16 v[30:33], v[212:215], v[150:153], v[30:33]
	v_mfma_f32_16x16x32_bf16 v[54:57], v[212:215], v[196:199], v[54:57]
	v_mfma_f32_16x16x32_bf16 v[26:29], v[220:223], v[150:153], v[26:29]
	v_mfma_f32_16x16x32_bf16 v[50:53], v[220:223], v[196:199], v[50:53]
	v_mfma_f32_16x16x32_bf16 v[42:45], v[228:231], v[150:153], v[42:45]
	v_mfma_f32_16x16x32_bf16 v[46:49], v[228:231], v[196:199], v[46:49]
	s_setprio 0
	s_barrier
	s_sub_i32 s96, s9, 64
	s_add_i32 s35, s8, 4
	s_and_b32 s96, s96, 0x180
	s_and_b32 s35, s35, 24
	s_lshl_b32 vcc_lo, s96, 1
	s_cmp_eq_u32 s35, 8
	s_cselect_b32 s96, s25, s3
	s_cselect_b32 s35, s82, s34
	s_cselect_b32 vcc_hi, s24, s2
	s_cselect_b32 s44, s15, s26
	s_add_u32 s96, s96, vcc_lo
	s_addc_u32 s97, s35, 0
	v_readfirstlane_b32 s35, v159
	v_lshl_add_u64 v[172:173], s[96:97], 0, v[134:135]
	s_mov_b32 m0, s35
	v_readfirstlane_b32 s35, v160
	ds_read_b128 v[232:235], v188
	ds_read_b128 v[236:239], v188 offset:1024
	ds_read_b128 v[240:243], v188 offset:2048
	ds_read_b128 v[244:247], v188 offset:3072
	global_load_lds_dwordx4 v[172:173], off
	v_lshl_add_u64 v[172:173], s[96:97], 0, v[136:137]
	s_mov_b32 m0, s35
	s_nop 0
	global_load_lds_dwordx4 v[172:173], off
	s_barrier
	s_waitcnt lgkmcnt(0)
	s_setprio 1
	s_waitcnt lgkmcnt(0)
	v_mfma_f32_16x16x32_bf16 v[74:77], v[200:203], v[232:235], v[74:77]
	v_mfma_f32_16x16x32_bf16 v[90:93], v[200:203], v[240:243], v[90:93]
	v_mfma_f32_16x16x32_bf16 v[70:73], v[208:211], v[232:235], v[70:73]
	v_mfma_f32_16x16x32_bf16 v[86:89], v[208:211], v[240:243], v[86:89]
	v_mfma_f32_16x16x32_bf16 v[66:69], v[216:219], v[232:235], v[66:69]
	v_mfma_f32_16x16x32_bf16 v[82:85], v[216:219], v[240:243], v[82:85]
	v_mfma_f32_16x16x32_bf16 v[62:65], v[224:227], v[232:235], v[62:65]
	v_mfma_f32_16x16x32_bf16 v[78:81], v[224:227], v[240:243], v[78:81]
	v_mfma_f32_16x16x32_bf16 v[74:77], v[204:207], v[236:239], v[74:77]
	v_mfma_f32_16x16x32_bf16 v[90:93], v[204:207], v[244:247], v[90:93]
	v_mfma_f32_16x16x32_bf16 v[70:73], v[212:215], v[236:239], v[70:73]
	v_mfma_f32_16x16x32_bf16 v[86:89], v[212:215], v[244:247], v[86:89]
	v_mfma_f32_16x16x32_bf16 v[66:69], v[220:223], v[236:239], v[66:69]
	v_mfma_f32_16x16x32_bf16 v[82:85], v[220:223], v[244:247], v[82:85]
	v_mfma_f32_16x16x32_bf16 v[62:65], v[228:231], v[236:239], v[62:65]
	v_mfma_f32_16x16x32_bf16 v[78:81], v[228:231], v[244:247], v[78:81]
	s_setprio 0
	s_add_u32 vcc_lo, s44, vcc_lo
	s_addc_u32 vcc_hi, vcc_hi, 0
	v_readfirstlane_b32 s35, v158
	v_lshl_add_u64 v[172:173], vcc, 0, v[134:135]
	s_mov_b32 m0, s35
	v_readfirstlane_b32 s35, v164
	s_barrier
	ds_read_b128 v[200:203], v157 offset:16384
	ds_read_b128 v[204:207], v157 offset:17408
	ds_read_b128 v[208:211], v156 offset:16384
	ds_read_b128 v[212:215], v156 offset:17408
	ds_read_b128 v[216:219], v155 offset:16384
	ds_read_b128 v[220:223], v155 offset:17408
	ds_read_b128 v[224:227], v154 offset:16384
	ds_read_b128 v[228:231], v154 offset:17408
	global_load_lds_dwordx4 v[172:173], off
	v_lshl_add_u64 v[172:173], vcc, 0, v[136:137]
	s_mov_b32 m0, s35
	s_nop 0
	global_load_lds_dwordx4 v[172:173], off
	s_barrier
	s_waitcnt lgkmcnt(0)
	s_setprio 1
	s_waitcnt lgkmcnt(0)
	v_mfma_f32_16x16x32_bf16 v[106:109], v[200:203], v[146:149], v[106:109]
	v_mfma_f32_16x16x32_bf16 v[122:125], v[200:203], v[192:195], v[122:125]
	v_mfma_f32_16x16x32_bf16 v[102:105], v[208:211], v[146:149], v[102:105]
	v_mfma_f32_16x16x32_bf16 v[118:121], v[208:211], v[192:195], v[118:121]
	v_mfma_f32_16x16x32_bf16 v[98:101], v[216:219], v[146:149], v[98:101]
	v_mfma_f32_16x16x32_bf16 v[114:117], v[216:219], v[192:195], v[114:117]
	v_mfma_f32_16x16x32_bf16 v[94:97], v[224:227], v[146:149], v[94:97]
	v_mfma_f32_16x16x32_bf16 v[110:113], v[224:227], v[192:195], v[110:113]
	v_mfma_f32_16x16x32_bf16 v[106:109], v[204:207], v[150:153], v[106:109]
	v_mfma_f32_16x16x32_bf16 v[122:125], v[204:207], v[196:199], v[122:125]
	v_mfma_f32_16x16x32_bf16 v[102:105], v[212:215], v[150:153], v[102:105]
	v_mfma_f32_16x16x32_bf16 v[118:121], v[212:215], v[196:199], v[118:121]
	v_mfma_f32_16x16x32_bf16 v[98:101], v[220:223], v[150:153], v[98:101]
	v_mfma_f32_16x16x32_bf16 v[114:117], v[220:223], v[196:199], v[114:117]
	v_mfma_f32_16x16x32_bf16 v[94:97], v[228:231], v[150:153], v[94:97]
	v_mfma_f32_16x16x32_bf16 v[110:113], v[228:231], v[196:199], v[110:113]
	s_setprio 0
	s_barrier
; #define STAGE(P, BASE, br, kt) do { const bf16_t* g_ = (BASE) + (size_t)(br) * K + (size_t)(kt) * 64; \
;         _Pragma("unroll") for (int i_ = 0; i_ < 2; ++i_) \
;             __builtin_amdgcn_global_load_lds((const unsigned*)(g_ + gofs[i_]), (lds_ptr_t)((P) + wb + i_ * 8192), 16, 0, 0); } while (0)
; #define LDA(dst, b, hh) _Pragma("unroll") for (int m = 0; m < 4; ++m) _Pragma("unroll") for (int k = 0; k < 2; ++k) \
;         dst[m][k] = *(const bf16x8*)(SA(b, hh) + lds_byte(wr * 64 + m * 16 + fr, k * 32 + fq * 8))
; #define LDB(dst, b, hh) _Pragma("unroll") for (int n = 0; n < 2; ++n) _Pragma("unroll") for (int k = 0; k < 2; ++k) \
;         dst[n][k] = *(const bf16x8*)(SB(b, hh) + lds_byte(wc * 32 + n * 16 + fr, k * 32 + fq * 8))
; #define MMA(ai, bj, At_, Bt_) do { __builtin_amdgcn_s_setprio(1); \
;         _Pragma("unroll") for (int m = 0; m < 4; ++m) _Pragma("unroll") for (int n = 0; n < 2; ++n) _Pragma("unroll") for (int k = 0; k < 2; ++k) \
;             acc[ai][bj][m][n] = MFMA16(At_[m][k], Bt_[n][k], acc[ai][bj][m][n]); \
;         __builtin_amdgcn_s_setprio(0); } while (0)
; #define WAIT_L(n) asm volatile("s_waitcnt lgkmcnt(" #n ")" ::: "memory")
; #define BAR __builtin_amdgcn_s_barrier()
; #define SCHED __builtin_amdgcn_sched_barrier(0)
; #define STAGE(P, BASE, br, kt) do { const int sg_ = (kt) >> 3; const bf16_t* g_ = (sg_ == 0 ? BASE##0 : sg_ == 1 ? BASE##1 : BASE##2) + (size_t)(br) * K + (size_t)((kt) & 7) * 64; \
;         _Pragma("unroll") for (int i_ = 0; i_ < 2; ++i_) \
;             __builtin_amdgcn_global_load_lds((const unsigned*)(g_ + gofs[i_]), (lds_ptr_t)((P) + wb + i_ * 8192), 16, 0, 0); } while (0)
; #define WAIT_L(n) asm volatile("s_waitcnt lgkmcnt(" #n ")" ::: "memory")
; #define BAR __builtin_amdgcn_s_barrier()
; template <class Hook>
; DI void gemm8_cat3(f32x4 (&acc)[2][2][4][2], const bf16_t* R0, const bf16_t* R1, const bf16_t* R2, const bf16_t* C0, const bf16_t* C1, const bf16_t* C2, char* shm, Hook hook) {
;     ...
;         LDB(B0, 1, 0); SCHED; LDA(At, 1, 0); STAGE(SA(0, 1), R, 128, tt + 2);
;         WAIT_L(8); BAR; WAIT_L(0); MMA(0, 0, At, B0); BAR; SCHED;
;         LDB(B1, 1, 1); STAGE(SB(1, 0), C, 0, tt + 3);
;         BAR; WAIT_L(0); MMA(0, 1, At, B1); BAR;
;         LDA(At, 1, 1); STAGE(SA(1, 0), R, 0, tt + 3);
;         BAR; WAIT_L(0); MMA(1, 0, At, B0); BAR; SCHED;
;         STAGE(SB(1, 1), C, 128, tt + 3);
	s_add_u32 s96, s96, 0x20000
	s_addc_u32 s97, s97, 0
	v_readfirstlane_b32 s35, v165
	v_lshl_add_u64 v[146:147], s[96:97], 0, v[134:135]
	s_mov_b32 m0, s35
	v_readfirstlane_b32 s35, v166
	global_load_lds_dwordx4 v[146:147], off
	v_lshl_add_u64 v[146:147], s[96:97], 0, v[136:137]
	s_mov_b32 m0, s35
	s_nop 0
	global_load_lds_dwordx4 v[146:147], off
	s_waitcnt vmcnt(6)
	s_barrier
	s_setprio 1
	v_mfma_f32_16x16x32_bf16 v[126:129], v[200:203], v[232:235], v[126:129]
	v_mfma_f32_16x16x32_bf16 v[14:17], v[200:203], v[240:243], v[14:17]
	v_mfma_f32_16x16x32_bf16 v[34:37], v[208:211], v[232:235], v[34:37]
	v_mfma_f32_16x16x32_bf16 v[6:9], v[208:211], v[240:243], v[6:9]
	v_mfma_f32_16x16x32_bf16 v[38:41], v[216:219], v[232:235], v[38:41]
	v_mfma_f32_16x16x32_bf16 v[10:13], v[216:219], v[240:243], v[10:13]
	v_mfma_f32_16x16x32_bf16 v[22:25], v[224:227], v[232:235], v[22:25]
	v_mfma_f32_16x16x32_bf16 v[2:5], v[224:227], v[240:243], v[2:5]
	v_mfma_f32_16x16x32_bf16 v[126:129], v[204:207], v[236:239], v[126:129]
	v_mfma_f32_16x16x32_bf16 v[14:17], v[204:207], v[244:247], v[14:17]
	v_mfma_f32_16x16x32_bf16 v[34:37], v[212:215], v[236:239], v[34:37]
	v_mfma_f32_16x16x32_bf16 v[6:9], v[212:215], v[244:247], v[6:9]
	v_mfma_f32_16x16x32_bf16 v[38:41], v[220:223], v[236:239], v[38:41]
	v_mfma_f32_16x16x32_bf16 v[10:13], v[220:223], v[244:247], v[10:13]
	v_mfma_f32_16x16x32_bf16 v[22:25], v[228:231], v[236:239], v[22:25]
	v_mfma_f32_16x16x32_bf16 v[2:5], v[228:231], v[244:247], v[2:5]
	s_setprio 0
	s_barrier
	ds_read_b128 v[146:149], v169
	ds_read_b128 v[150:153], v169 offset:1024
	ds_read_b128 v[192:195], v169 offset:2048
	ds_read_b128 v[196:199], v169 offset:3072
	s_add_u32 s96, vcc_lo, 0x20000
	s_addc_u32 s97, vcc_hi, 0
	v_readfirstlane_b32 s35, v167
	v_lshl_add_u64 v[172:173], s[96:97], 0, v[134:135]
	s_mov_b32 m0, s35
	v_readfirstlane_b32 s35, v168
	ds_read_b128 v[200:203], v157 offset:32768
	ds_read_b128 v[204:207], v157 offset:33792
	ds_read_b128 v[208:211], v156 offset:32768
	ds_read_b128 v[212:215], v156 offset:33792
	ds_read_b128 v[216:219], v155 offset:32768
	ds_read_b128 v[220:223], v155 offset:33792
	ds_read_b128 v[224:227], v154 offset:32768
	ds_read_b128 v[228:231], v154 offset:33792
	global_load_lds_dwordx4 v[172:173], off
	v_lshl_add_u64 v[172:173], s[96:97], 0, v[136:137]
	s_mov_b32 m0, s35
	s_nop 0
	global_load_lds_dwordx4 v[172:173], off
	s_waitcnt lgkmcnt(8)
	s_barrier
	s_waitcnt lgkmcnt(0)
	s_setprio 1
	s_waitcnt lgkmcnt(0)
	v_mfma_f32_16x16x32_bf16 v[18:21], v[200:203], v[146:149], v[18:21]
	v_mfma_f32_16x16x32_bf16 v[58:61], v[200:203], v[192:195], v[58:61]
	v_mfma_f32_16x16x32_bf16 v[30:33], v[208:211], v[146:149], v[30:33]
	v_mfma_f32_16x16x32_bf16 v[54:57], v[208:211], v[192:195], v[54:57]
	v_mfma_f32_16x16x32_bf16 v[26:29], v[216:219], v[146:149], v[26:29]
	v_mfma_f32_16x16x32_bf16 v[50:53], v[216:219], v[192:195], v[50:53]
	v_mfma_f32_16x16x32_bf16 v[42:45], v[224:227], v[146:149], v[42:45]
	v_mfma_f32_16x16x32_bf16 v[46:49], v[224:227], v[192:195], v[46:49]
	v_mfma_f32_16x16x32_bf16 v[18:21], v[204:207], v[150:153], v[18:21]
	v_mfma_f32_16x16x32_bf16 v[58:61], v[204:207], v[196:199], v[58:61]
	v_mfma_f32_16x16x32_bf16 v[30:33], v[212:215], v[150:153], v[30:33]
	v_mfma_f32_16x16x32_bf16 v[54:57], v[212:215], v[196:199], v[54:57]
	v_mfma_f32_16x16x32_bf16 v[26:29], v[220:223], v[150:153], v[26:29]
	v_mfma_f32_16x16x32_bf16 v[50:53], v[220:223], v[196:199], v[50:53]
	v_mfma_f32_16x16x32_bf16 v[42:45], v[228:231], v[150:153], v[42:45]
	v_mfma_f32_16x16x32_bf16 v[46:49], v[228:231], v[196:199], v[46:49]
	s_setprio 0
	s_barrier
	s_add_i32 s35, s8, 5
	s_and_b32 s44, s9, 0x1c0
	s_and_b32 s35, s35, 24
	s_lshl_b32 s44, s44, 1
	s_cmp_eq_u32 s35, 8
	s_cselect_b32 s45, s25, s3
	s_cselect_b32 s35, s82, s34
	s_cselect_b32 vcc_hi, s24, s2
	s_cselect_b32 vcc_lo, s15, s26
	s_add_u32 s96, s45, s44
	s_addc_u32 s97, s35, 0
	v_readfirstlane_b32 s35, v170
	v_lshl_add_u64 v[172:173], s[96:97], 0, v[134:135]
	s_mov_b32 m0, s35
	v_readfirstlane_b32 s35, v171
	ds_read_b128 v[232:235], v161
	ds_read_b128 v[236:239], v161 offset:1024
	ds_read_b128 v[240:243], v161 offset:2048
	ds_read_b128 v[244:247], v161 offset:3072
	global_load_lds_dwordx4 v[172:173], off
	v_lshl_add_u64 v[172:173], s[96:97], 0, v[136:137]
	s_mov_b32 m0, s35
	s_nop 0
	global_load_lds_dwordx4 v[172:173], off
	s_barrier
	s_waitcnt lgkmcnt(0)
	s_setprio 1
	s_waitcnt lgkmcnt(0)
	v_mfma_f32_16x16x32_bf16 v[74:77], v[200:203], v[232:235], v[74:77]
	v_mfma_f32_16x16x32_bf16 v[90:93], v[200:203], v[240:243], v[90:93]
	v_mfma_f32_16x16x32_bf16 v[70:73], v[208:211], v[232:235], v[70:73]
	v_mfma_f32_16x16x32_bf16 v[86:89], v[208:211], v[240:243], v[86:89]
	v_mfma_f32_16x16x32_bf16 v[66:69], v[216:219], v[232:235], v[66:69]
	v_mfma_f32_16x16x32_bf16 v[82:85], v[216:219], v[240:243], v[82:85]
	v_mfma_f32_16x16x32_bf16 v[62:65], v[224:227], v[232:235], v[62:65]
	v_mfma_f32_16x16x32_bf16 v[78:81], v[224:227], v[240:243], v[78:81]
	v_mfma_f32_16x16x32_bf16 v[74:77], v[204:207], v[236:239], v[74:77]
	v_mfma_f32_16x16x32_bf16 v[90:93], v[204:207], v[244:247], v[90:93]
	v_mfma_f32_16x16x32_bf16 v[70:73], v[212:215], v[236:239], v[70:73]
	v_mfma_f32_16x16x32_bf16 v[86:89], v[212:215], v[244:247], v[86:89]
	v_mfma_f32_16x16x32_bf16 v[66:69], v[220:223], v[236:239], v[66:69]
	v_mfma_f32_16x16x32_bf16 v[82:85], v[220:223], v[244:247], v[82:85]
	v_mfma_f32_16x16x32_bf16 v[62:65], v[228:231], v[236:239], v[62:65]
	v_mfma_f32_16x16x32_bf16 v[78:81], v[228:231], v[244:247], v[78:81]
	s_setprio 0
	s_add_u32 vcc_lo, vcc_lo, s44
	s_addc_u32 vcc_hi, vcc_hi, 0
	v_readfirstlane_b32 s35, v184
	v_lshl_add_u64 v[172:173], vcc, 0, v[134:135]
	s_mov_b32 m0, s35
	v_readfirstlane_b32 s35, v185
	s_barrier
; DI float frcp(float x) { return __builtin_amdgcn_rcpf(x); }
; #define STAGE(P, BASE, br, kt) do { const bf16_t* g_ = (BASE) + (size_t)(br) * K + (size_t)(kt) * 64; \
;         _Pragma("unroll") for (int i_ = 0; i_ < 2; ++i_) \
;             __builtin_amdgcn_global_load_lds((const unsigned*)(g_ + gofs[i_]), (lds_ptr_t)((P) + wb + i_ * 8192), 16, 0, 0); } while (0)
; #define LDA(dst, b, hh) _Pragma("unroll") for (int m = 0; m < 4; ++m) _Pragma("unroll") for (int k = 0; k < 2; ++k) \
;         dst[m][k] = *(const bf16x8*)(SA(b, hh) + lds_byte(wr * 64 + m * 16 + fr, k * 32 + fq * 8))
; #define MMA(ai, bj, At_, Bt_) do { __builtin_amdgcn_s_setprio(1); \
;         _Pragma("unroll") for (int m = 0; m < 4; ++m) _Pragma("unroll") for (int n = 0; n < 2; ++n) _Pragma("unroll") for (int k = 0; k < 2; ++k) \
;             acc[ai][bj][m][n] = MFMA16(At_[m][k], Bt_[n][k], acc[ai][bj][m][n]); \
;         __builtin_amdgcn_s_setprio(0); } while (0)
; #define WAIT_V(n) asm volatile("s_waitcnt vmcnt(" #n ")" ::: "memory")
; #define WAIT_L(n) asm volatile("s_waitcnt lgkmcnt(" #n ")" ::: "memory")
; #define BAR __builtin_amdgcn_s_barrier()
; template <class Hook>
; DI void gemm8_cat3(f32x4 (&acc)[2][2][4][2], const bf16_t* R0, const bf16_t* R1, const bf16_t* R2, const bf16_t* C0, const bf16_t* C1, const bf16_t* C2, char* shm, Hook hook) {
;     ...
;         LDA(At, 1, 1); STAGE(SA(1, 0), R, 0, tt + 3);
;         BAR; WAIT_L(0); MMA(1, 0, At, B0); BAR; SCHED;
;         STAGE(SB(1, 1), C, 128, tt + 3);
;         WAIT_V(6); BAR; MMA(1, 1, At, B1); BAR;
;     }
;     hook(1);
; DI void merge_scale(const Params& P, int tile, int seg, f32x4 (&acc)[2][2][4][2]) {
; #pragma unroll
;     for (int g8 = 0; g8 < 8; ++g8) {
;         const int ai = g8 >> 2, bj = (g8 >> 1) & 1, nn = g8 & 1;
;         const u32x4 ga = *gate_slot(P, tile, seg, g8), gb = *gate_slot(P, tile, seg + 1, g8);
; #pragma unroll
;         for (int e = 0; e < 8; ++e) {
;             const float rl = (float)((ga[e >> 2] >> (8 * (e & 3))) & 255u) * frcp((float)((gb[e >> 2] >> (8 * (e & 3))) & 255u));
;             const float rh = (float)((ga[2 + (e >> 2)] >> (8 * (e & 3))) & 255u) * frcp((float)((gb[2 + (e >> 2)] >> (8 * (e & 3))) & 255u));
;             acc[ai][bj][e >> 2][nn][e & 3] *= rl;
;             acc[ai][bj][2 + (e >> 2)][nn][e & 3] *= rh;
;         }
;         __builtin_amdgcn_sched_barrier(0);
;     }
; }
	ds_read_b128 v[200:203], v157 offset:49152
	ds_read_b128 v[204:207], v157 offset:50176
	ds_read_b128 v[208:211], v156 offset:49152
	ds_read_b128 v[212:215], v156 offset:50176
	ds_read_b128 v[216:219], v155 offset:49152
	ds_read_b128 v[220:223], v155 offset:50176
	ds_read_b128 v[224:227], v154 offset:49152
	ds_read_b128 v[228:231], v154 offset:50176
	global_load_lds_dwordx4 v[172:173], off
	v_lshl_add_u64 v[172:173], vcc, 0, v[136:137]
	s_mov_b32 m0, s35
	s_nop 0
	global_load_lds_dwordx4 v[172:173], off
	s_barrier
	s_waitcnt lgkmcnt(0)
	s_setprio 1
	s_waitcnt lgkmcnt(0)
	v_mfma_f32_16x16x32_bf16 v[106:109], v[200:203], v[146:149], v[106:109]
	v_mfma_f32_16x16x32_bf16 v[122:125], v[200:203], v[192:195], v[122:125]
	v_mfma_f32_16x16x32_bf16 v[102:105], v[208:211], v[146:149], v[102:105]
	v_mfma_f32_16x16x32_bf16 v[118:121], v[208:211], v[192:195], v[118:121]
	v_mfma_f32_16x16x32_bf16 v[98:101], v[216:219], v[146:149], v[98:101]
	v_mfma_f32_16x16x32_bf16 v[114:117], v[216:219], v[192:195], v[114:117]
	v_mfma_f32_16x16x32_bf16 v[94:97], v[224:227], v[146:149], v[94:97]
	v_mfma_f32_16x16x32_bf16 v[110:113], v[224:227], v[192:195], v[110:113]
	v_mfma_f32_16x16x32_bf16 v[106:109], v[204:207], v[150:153], v[106:109]
	v_mfma_f32_16x16x32_bf16 v[122:125], v[204:207], v[196:199], v[122:125]
	v_mfma_f32_16x16x32_bf16 v[102:105], v[212:215], v[150:153], v[102:105]
	v_mfma_f32_16x16x32_bf16 v[118:121], v[212:215], v[196:199], v[118:121]
	v_mfma_f32_16x16x32_bf16 v[98:101], v[220:223], v[150:153], v[98:101]
	v_mfma_f32_16x16x32_bf16 v[114:117], v[220:223], v[196:199], v[114:117]
	v_mfma_f32_16x16x32_bf16 v[94:97], v[228:231], v[150:153], v[94:97]
	v_mfma_f32_16x16x32_bf16 v[110:113], v[228:231], v[196:199], v[110:113]
	s_setprio 0
	s_barrier
	s_add_u32 s96, s96, 0x20000
	s_addc_u32 s97, s97, 0
	v_readfirstlane_b32 s35, v186
	v_lshl_add_u64 v[146:147], s[96:97], 0, v[134:135]
	s_mov_b32 m0, s35
	v_readfirstlane_b32 s35, v187
	global_load_lds_dwordx4 v[146:147], off
	v_lshl_add_u64 v[146:147], s[96:97], 0, v[136:137]
	s_mov_b32 m0, s35
	s_nop 0
	global_load_lds_dwordx4 v[146:147], off
	s_waitcnt vmcnt(6)
	s_barrier
	s_setprio 1
	v_mfma_f32_16x16x32_bf16 v[126:129], v[200:203], v[232:235], v[126:129]
	v_mfma_f32_16x16x32_bf16 v[14:17], v[200:203], v[240:243], v[14:17]
	v_mfma_f32_16x16x32_bf16 v[34:37], v[208:211], v[232:235], v[34:37]
	v_mfma_f32_16x16x32_bf16 v[6:9], v[208:211], v[240:243], v[6:9]
	v_mfma_f32_16x16x32_bf16 v[38:41], v[216:219], v[232:235], v[38:41]
	v_mfma_f32_16x16x32_bf16 v[10:13], v[216:219], v[240:243], v[10:13]
	v_mfma_f32_16x16x32_bf16 v[22:25], v[224:227], v[232:235], v[22:25]
	v_mfma_f32_16x16x32_bf16 v[2:5], v[224:227], v[240:243], v[2:5]
	v_mfma_f32_16x16x32_bf16 v[126:129], v[204:207], v[236:239], v[126:129]
	v_mfma_f32_16x16x32_bf16 v[14:17], v[204:207], v[244:247], v[14:17]
	v_mfma_f32_16x16x32_bf16 v[34:37], v[212:215], v[236:239], v[34:37]
	v_mfma_f32_16x16x32_bf16 v[6:9], v[212:215], v[244:247], v[6:9]
	v_mfma_f32_16x16x32_bf16 v[38:41], v[220:223], v[236:239], v[38:41]
	v_mfma_f32_16x16x32_bf16 v[10:13], v[220:223], v[244:247], v[10:13]
	v_mfma_f32_16x16x32_bf16 v[22:25], v[228:231], v[236:239], v[22:25]
	v_mfma_f32_16x16x32_bf16 v[2:5], v[228:231], v[244:247], v[2:5]
	s_setprio 0
	s_add_i32 s8, s8, 2
	s_addk_i32 s9, 0x80
	v_lshl_add_u64 v[130:131], v[130:131], 0, s[90:91]
	s_cmp_lt_u32 s8, 14
	v_lshl_add_u64 v[132:133], v[132:133], 0, s[90:91]
	s_barrier
	s_cbranch_scc1 .LBB0_58
	s_lshl_b64 s[8:9], s[58:59], 16
	v_mov_b32_e32 v130, v162
	s_add_u32 s35, s8, 0x20000
	s_addc_u32 s44, s9, 0
	v_ashrrev_i32_e32 v131, 31, v130
	v_lshl_add_u64 v[130:131], v[130:131], 4, s[56:57]
	v_mov_b32_e32 v134, v162
	s_add_u32 s8, s74, s35
	global_load_dwordx4 v[130:133], v[130:131], off
	s_addc_u32 s9, s75, s44
	v_ashrrev_i32_e32 v135, 31, v134
	v_lshl_add_u64 v[134:135], v[134:135], 4, s[8:9]
	global_load_dwordx4 v[134:137], v[134:135], off
	s_waitcnt vmcnt(1)
	v_cvt_f32_ubyte3_e32 v147, v130
	v_cvt_f32_ubyte2_e32 v146, v130
	v_cvt_f32_ubyte1_e32 v149, v130
	v_cvt_f32_ubyte0_e32 v148, v130
	v_cvt_f32_ubyte3_e32 v151, v132
	v_cvt_f32_ubyte2_e32 v150, v132
	v_cvt_f32_ubyte1_e32 v153, v132
	v_cvt_f32_ubyte0_e32 v152, v132
	v_cvt_f32_ubyte3_e32 v173, v131
	v_cvt_f32_ubyte2_e32 v172, v131
	v_cvt_f32_ubyte1_e32 v193, v131
	v_cvt_f32_ubyte0_e32 v192, v131
	v_cvt_f32_ubyte3_e32 v131, v133
	v_cvt_f32_ubyte2_e32 v130, v133
	v_cvt_f32_ubyte1_e32 v195, v133
	v_cvt_f32_ubyte0_e32 v194, v133
	s_waitcnt vmcnt(0)
	v_cvt_f32_ubyte0_e32 v132, v134
	v_cvt_f32_ubyte0_e32 v133, v136
	v_cvt_f32_ubyte1_e32 v196, v134
	v_cvt_f32_ubyte1_e32 v197, v136
	v_cvt_f32_ubyte2_e32 v198, v134
	v_cvt_f32_ubyte2_e32 v199, v136
	v_cvt_f32_ubyte3_e32 v200, v134
	v_cvt_f32_ubyte3_e32 v201, v136
	v_cvt_f32_ubyte0_e32 v202, v135
	v_cvt_f32_ubyte0_e32 v203, v137
	v_cvt_f32_ubyte1_e32 v204, v135
	v_cvt_f32_ubyte1_e32 v205, v137
	v_cvt_f32_ubyte2_e32 v206, v135
	v_cvt_f32_ubyte2_e32 v207, v137
	v_cvt_f32_ubyte3_e32 v208, v135
	v_cvt_f32_ubyte3_e32 v209, v137
	v_rcp_iflag_f32_e32 v132, v132
	v_rcp_iflag_f32_e32 v134, v133
	v_rcp_iflag_f32_e32 v133, v196
	v_rcp_iflag_f32_e32 v135, v197
	v_rcp_iflag_f32_e32 v136, v198
	v_rcp_iflag_f32_e32 v196, v199
	v_rcp_iflag_f32_e32 v137, v200
	v_rcp_iflag_f32_e32 v197, v201
	v_rcp_iflag_f32_e32 v198, v202
	v_rcp_iflag_f32_e32 v200, v203
	v_rcp_iflag_f32_e32 v199, v204
	v_rcp_iflag_f32_e32 v201, v205
	v_rcp_iflag_f32_e32 v202, v206
	v_rcp_iflag_f32_e32 v204, v207
	v_rcp_iflag_f32_e32 v203, v208
	v_rcp_iflag_f32_e32 v205, v209
	v_pk_mul_f32 v[148:149], v[132:133], v[148:149]
	v_pk_mul_f32 v[132:133], v[136:137], v[146:147]
	v_pk_mul_f32 v[134:135], v[134:135], v[152:153]
	v_pk_mul_f32 v[136:137], v[196:197], v[150:151]
	v_pk_mul_f32 v[146:147], v[198:199], v[192:193]
	v_pk_mul_f32 v[150:151], v[202:203], v[172:173]
	v_pk_mul_f32 v[152:153], v[200:201], v[194:195]
	v_pk_mul_f32 v[172:173], v[204:205], v[130:131]
	v_pk_mul_f32 v[132:133], v[20:21], v[132:133]
	v_pk_mul_f32 v[130:131], v[18:19], v[148:149]
	v_pk_mul_f32 v[20:21], v[28:29], v[136:137]
	v_pk_mul_f32 v[18:19], v[26:27], v[134:135]
	v_pk_mul_f32 v[32:33], v[32:33], v[150:151]
	v_pk_mul_f32 v[30:31], v[30:31], v[146:147]
	v_pk_mul_f32 v[28:29], v[44:45], v[172:173]
	v_pk_mul_f32 v[26:27], v[42:43], v[152:153]
	v_mov_b32_e32 v42, v162
	s_add_u32 s35, s62, s35
	v_ashrrev_i32_e32 v43, 31, v42
	v_lshl_add_u64 v[42:43], v[42:43], 4, s[54:55]
	s_addc_u32 vcc_lo, s63, s44
	global_load_dwordx4 v[134:137], v[42:43], off
	s_add_u32 s58, s35, 0x13802000
	v_mov_b32_e32 v42, v162
	s_addc_u32 s59, vcc_lo, 0
	v_ashrrev_i32_e32 v43, 31, v42
	v_lshl_add_u64 v[42:43], v[42:43], 4, s[58:59]
	global_load_dwordx4 v[146:149], v[42:43], off
	s_waitcnt vmcnt(1)
; DI float frcp(float x) { return __builtin_amdgcn_rcpf(x); }
; DI u32x4* gate_slot(const Params& P, int tile, int j, int g8) { return (u32x4*)slotp(P, SL_SK) + ((size_t)(tile * 3 + j) * 8 + g8) * 512 + tid(); }
; DI void merge_scale(const Params& P, int tile, int seg, f32x4 (&acc)[2][2][4][2]) {
; #pragma unroll
;     for (int g8 = 0; g8 < 8; ++g8) {
;         const int ai = g8 >> 2, bj = (g8 >> 1) & 1, nn = g8 & 1;
;         const u32x4 ga = *gate_slot(P, tile, seg, g8), gb = *gate_slot(P, tile, seg + 1, g8);
; #pragma unroll
;         for (int e = 0; e < 8; ++e) {
;             const float rl = (float)((ga[e >> 2] >> (8 * (e & 3))) & 255u) * frcp((float)((gb[e >> 2] >> (8 * (e & 3))) & 255u));
;             const float rh = (float)((ga[2 + (e >> 2)] >> (8 * (e & 3))) & 255u) * frcp((float)((gb[2 + (e >> 2)] >> (8 * (e & 3))) & 255u));
;             acc[ai][bj][e >> 2][nn][e & 3] *= rl;
;             acc[ai][bj][2 + (e >> 2)][nn][e & 3] *= rh;
;         }
;         __builtin_amdgcn_sched_barrier(0);
;     }
; }
	v_cvt_f32_ubyte3_e32 v173, v134
	v_cvt_f32_ubyte2_e32 v172, v134
	v_cvt_f32_ubyte1_e32 v193, v134
	v_cvt_f32_ubyte0_e32 v192, v134
	s_waitcnt vmcnt(0)
	v_cvt_f32_ubyte0_e32 v43, v148
	v_cvt_f32_ubyte1_e32 v44, v148
	v_cvt_f32_ubyte2_e32 v45, v148
	v_cvt_f32_ubyte0_e32 v42, v146
	v_rcp_iflag_f32_e32 v150, v43
	v_cvt_f32_ubyte1_e32 v43, v146
	v_rcp_iflag_f32_e32 v151, v44
	v_cvt_f32_ubyte2_e32 v44, v146
	v_rcp_iflag_f32_e32 v152, v45
	v_cvt_f32_ubyte3_e32 v45, v146
	v_rcp_iflag_f32_e32 v42, v42
	v_rcp_iflag_f32_e32 v43, v43
	v_rcp_iflag_f32_e32 v44, v44
	v_rcp_iflag_f32_e32 v45, v45
	v_cvt_f32_ubyte3_e32 v146, v148
	v_rcp_iflag_f32_e32 v153, v146
	v_pk_mul_f32 v[42:43], v[42:43], v[192:193]
	v_pk_mul_f32 v[44:45], v[44:45], v[172:173]
	v_pk_mul_f32 v[42:43], v[58:59], v[42:43]
	v_pk_mul_f32 v[44:45], v[60:61], v[44:45]
	v_cvt_f32_ubyte3_e32 v59, v136
	v_cvt_f32_ubyte2_e32 v58, v136
	v_cvt_f32_ubyte1_e32 v61, v136
	v_cvt_f32_ubyte0_e32 v60, v136
	v_pk_mul_f32 v[60:61], v[150:151], v[60:61]
	v_pk_mul_f32 v[58:59], v[152:153], v[58:59]
	v_pk_mul_f32 v[50:51], v[50:51], v[60:61]
	v_pk_mul_f32 v[52:53], v[52:53], v[58:59]
	v_cvt_f32_ubyte0_e32 v58, v147
	v_cvt_f32_ubyte1_e32 v59, v147
	v_cvt_f32_ubyte2_e32 v60, v147
	v_cvt_f32_ubyte3_e32 v61, v147
	v_rcp_iflag_f32_e32 v150, v58
	v_rcp_iflag_f32_e32 v151, v59
	v_rcp_iflag_f32_e32 v146, v60
	v_rcp_iflag_f32_e32 v147, v61
	v_cvt_f32_ubyte0_e32 v58, v149
	v_cvt_f32_ubyte1_e32 v59, v149
	v_cvt_f32_ubyte2_e32 v60, v149
	v_cvt_f32_ubyte3_e32 v61, v149
	v_rcp_iflag_f32_e32 v58, v58
	v_rcp_iflag_f32_e32 v59, v59
	v_rcp_iflag_f32_e32 v60, v60
	v_rcp_iflag_f32_e32 v61, v61
	v_cvt_f32_ubyte3_e32 v149, v135
	v_cvt_f32_ubyte2_e32 v148, v135
	v_cvt_f32_ubyte1_e32 v153, v135
	v_cvt_f32_ubyte0_e32 v152, v135
	v_pk_mul_f32 v[134:135], v[150:151], v[152:153]
	v_pk_mul_f32 v[146:147], v[146:147], v[148:149]
	v_pk_mul_f32 v[54:55], v[54:55], v[134:135]
	v_pk_mul_f32 v[56:57], v[56:57], v[146:147]
	v_cvt_f32_ubyte3_e32 v135, v137
	v_cvt_f32_ubyte2_e32 v134, v137
	v_cvt_f32_ubyte1_e32 v147, v137
	v_cvt_f32_ubyte0_e32 v146, v137
	v_pk_mul_f32 v[58:59], v[58:59], v[146:147]
	v_pk_mul_f32 v[60:61], v[60:61], v[134:135]
	v_pk_mul_f32 v[46:47], v[46:47], v[58:59]
	v_pk_mul_f32 v[48:49], v[48:49], v[60:61]
	v_mov_b32_e32 v58, v162
	s_add_u32 s56, s35, 0x13804000
	v_ashrrev_i32_e32 v59, 31, v58
	v_lshl_add_u64 v[58:59], v[58:59], 4, s[6:7]
	global_load_dwordx4 v[134:137], v[58:59], off
	v_mov_b32_e32 v58, v162
	s_addc_u32 s57, vcc_lo, 0
	v_ashrrev_i32_e32 v59, 31, v58
	v_lshl_add_u64 v[58:59], v[58:59], 4, s[56:57]
	global_load_dwordx4 v[146:149], v[58:59], off
	s_waitcnt vmcnt(1)
	v_cvt_f32_ubyte3_e32 v173, v134
	v_cvt_f32_ubyte2_e32 v172, v134
	v_cvt_f32_ubyte1_e32 v193, v134
	v_cvt_f32_ubyte0_e32 v192, v134
	s_waitcnt vmcnt(0)
	v_cvt_f32_ubyte0_e32 v59, v148
	v_cvt_f32_ubyte1_e32 v60, v148
	v_cvt_f32_ubyte2_e32 v61, v148
	v_cvt_f32_ubyte0_e32 v58, v146
	v_rcp_iflag_f32_e32 v150, v59
	v_cvt_f32_ubyte1_e32 v59, v146
	v_rcp_iflag_f32_e32 v151, v60
	v_cvt_f32_ubyte2_e32 v60, v146
	v_rcp_iflag_f32_e32 v152, v61
	v_cvt_f32_ubyte3_e32 v61, v146
	v_rcp_iflag_f32_e32 v58, v58
	v_rcp_iflag_f32_e32 v59, v59
	v_rcp_iflag_f32_e32 v60, v60
	v_rcp_iflag_f32_e32 v61, v61
	v_cvt_f32_ubyte3_e32 v146, v148
	v_rcp_iflag_f32_e32 v153, v146
	v_pk_mul_f32 v[58:59], v[58:59], v[192:193]
	v_pk_mul_f32 v[60:61], v[60:61], v[172:173]
	v_pk_mul_f32 v[58:59], v[74:75], v[58:59]
	v_pk_mul_f32 v[60:61], v[76:77], v[60:61]
	v_cvt_f32_ubyte3_e32 v75, v136
	v_cvt_f32_ubyte2_e32 v74, v136
	v_cvt_f32_ubyte1_e32 v77, v136
	v_cvt_f32_ubyte0_e32 v76, v136
	v_pk_mul_f32 v[76:77], v[150:151], v[76:77]
	v_pk_mul_f32 v[74:75], v[152:153], v[74:75]
	v_pk_mul_f32 v[66:67], v[66:67], v[76:77]
	v_pk_mul_f32 v[68:69], v[68:69], v[74:75]
	v_cvt_f32_ubyte0_e32 v74, v147
	v_cvt_f32_ubyte1_e32 v75, v147
	v_cvt_f32_ubyte2_e32 v76, v147
	v_cvt_f32_ubyte3_e32 v77, v147
	v_rcp_iflag_f32_e32 v150, v74
	v_rcp_iflag_f32_e32 v151, v75
	v_rcp_iflag_f32_e32 v146, v76
	v_rcp_iflag_f32_e32 v147, v77
	v_cvt_f32_ubyte0_e32 v74, v149
	v_cvt_f32_ubyte1_e32 v75, v149
	v_cvt_f32_ubyte2_e32 v76, v149
	v_cvt_f32_ubyte3_e32 v77, v149
	v_rcp_iflag_f32_e32 v74, v74
	v_rcp_iflag_f32_e32 v75, v75
	v_rcp_iflag_f32_e32 v76, v76
	v_rcp_iflag_f32_e32 v77, v77
	v_cvt_f32_ubyte3_e32 v149, v135
	v_cvt_f32_ubyte2_e32 v148, v135
	v_cvt_f32_ubyte1_e32 v153, v135
	v_cvt_f32_ubyte0_e32 v152, v135
	v_pk_mul_f32 v[134:135], v[150:151], v[152:153]
	v_pk_mul_f32 v[146:147], v[146:147], v[148:149]
	v_pk_mul_f32 v[70:71], v[70:71], v[134:135]
	v_pk_mul_f32 v[72:73], v[72:73], v[146:147]
	v_cvt_f32_ubyte3_e32 v135, v137
	v_cvt_f32_ubyte2_e32 v134, v137
	v_cvt_f32_ubyte1_e32 v147, v137
	v_cvt_f32_ubyte0_e32 v146, v137
	v_pk_mul_f32 v[74:75], v[74:75], v[146:147]
	v_pk_mul_f32 v[76:77], v[76:77], v[134:135]
	v_pk_mul_f32 v[62:63], v[62:63], v[74:75]
	v_pk_mul_f32 v[64:65], v[64:65], v[76:77]
	v_mov_b32_e32 v74, v162
	s_add_u32 s54, s35, 0x13806000
	v_ashrrev_i32_e32 v75, 31, v74
	v_lshl_add_u64 v[74:75], v[74:75], 4, s[10:11]
	global_load_dwordx4 v[134:137], v[74:75], off
	v_mov_b32_e32 v74, v162
	s_addc_u32 s55, vcc_lo, 0
	v_ashrrev_i32_e32 v75, 31, v74
	v_lshl_add_u64 v[74:75], v[74:75], 4, s[54:55]
	global_load_dwordx4 v[146:149], v[74:75], off
	s_waitcnt vmcnt(1)
	v_cvt_f32_ubyte3_e32 v173, v134
	v_cvt_f32_ubyte2_e32 v172, v134
	v_cvt_f32_ubyte1_e32 v193, v134
	v_cvt_f32_ubyte0_e32 v192, v134
	s_waitcnt vmcnt(0)
; DI float frcp(float x) { return __builtin_amdgcn_rcpf(x); }
; DI u32x4* gate_slot(const Params& P, int tile, int j, int g8) { return (u32x4*)slotp(P, SL_SK) + ((size_t)(tile * 3 + j) * 8 + g8) * 512 + tid(); }
; DI void merge_scale(const Params& P, int tile, int seg, f32x4 (&acc)[2][2][4][2]) {
; #pragma unroll
;     for (int g8 = 0; g8 < 8; ++g8) {
;         const int ai = g8 >> 2, bj = (g8 >> 1) & 1, nn = g8 & 1;
;         const u32x4 ga = *gate_slot(P, tile, seg, g8), gb = *gate_slot(P, tile, seg + 1, g8);
; #pragma unroll
;         for (int e = 0; e < 8; ++e) {
;             const float rl = (float)((ga[e >> 2] >> (8 * (e & 3))) & 255u) * frcp((float)((gb[e >> 2] >> (8 * (e & 3))) & 255u));
;             const float rh = (float)((ga[2 + (e >> 2)] >> (8 * (e & 3))) & 255u) * frcp((float)((gb[2 + (e >> 2)] >> (8 * (e & 3))) & 255u));
;             acc[ai][bj][e >> 2][nn][e & 3] *= rl;
;             acc[ai][bj][2 + (e >> 2)][nn][e & 3] *= rh;
;         }
;         __builtin_amdgcn_sched_barrier(0);
;     }
; }
	v_cvt_f32_ubyte0_e32 v75, v148
	v_cvt_f32_ubyte1_e32 v76, v148
	v_cvt_f32_ubyte2_e32 v77, v148
	v_cvt_f32_ubyte0_e32 v74, v146
	v_rcp_iflag_f32_e32 v150, v75
	v_cvt_f32_ubyte1_e32 v75, v146
	v_rcp_iflag_f32_e32 v151, v76
	v_cvt_f32_ubyte2_e32 v76, v146
	v_rcp_iflag_f32_e32 v152, v77
	v_cvt_f32_ubyte3_e32 v77, v146
	v_rcp_iflag_f32_e32 v74, v74
	v_rcp_iflag_f32_e32 v75, v75
	v_rcp_iflag_f32_e32 v76, v76
	v_rcp_iflag_f32_e32 v77, v77
	v_cvt_f32_ubyte3_e32 v146, v148
	v_rcp_iflag_f32_e32 v153, v146
	v_pk_mul_f32 v[74:75], v[74:75], v[192:193]
	v_pk_mul_f32 v[76:77], v[76:77], v[172:173]
	v_pk_mul_f32 v[74:75], v[90:91], v[74:75]
	v_pk_mul_f32 v[76:77], v[92:93], v[76:77]
	v_cvt_f32_ubyte3_e32 v91, v136
	v_cvt_f32_ubyte2_e32 v90, v136
	v_cvt_f32_ubyte1_e32 v93, v136
	v_cvt_f32_ubyte0_e32 v92, v136
	v_pk_mul_f32 v[92:93], v[150:151], v[92:93]
	v_pk_mul_f32 v[90:91], v[152:153], v[90:91]
	v_pk_mul_f32 v[82:83], v[82:83], v[92:93]
	v_pk_mul_f32 v[84:85], v[84:85], v[90:91]
	v_cvt_f32_ubyte0_e32 v90, v147
	v_cvt_f32_ubyte1_e32 v91, v147
	v_cvt_f32_ubyte2_e32 v92, v147
	v_cvt_f32_ubyte3_e32 v93, v147
	v_rcp_iflag_f32_e32 v150, v90
	v_rcp_iflag_f32_e32 v151, v91
	v_rcp_iflag_f32_e32 v146, v92
	v_rcp_iflag_f32_e32 v147, v93
	v_cvt_f32_ubyte0_e32 v90, v149
	v_cvt_f32_ubyte1_e32 v91, v149
	v_cvt_f32_ubyte2_e32 v92, v149
	v_cvt_f32_ubyte3_e32 v93, v149
	v_rcp_iflag_f32_e32 v90, v90
	v_rcp_iflag_f32_e32 v91, v91
	v_rcp_iflag_f32_e32 v92, v92
	v_rcp_iflag_f32_e32 v93, v93
	v_cvt_f32_ubyte3_e32 v149, v135
	v_cvt_f32_ubyte2_e32 v148, v135
	v_cvt_f32_ubyte1_e32 v153, v135
	v_cvt_f32_ubyte0_e32 v152, v135
	v_pk_mul_f32 v[134:135], v[150:151], v[152:153]
	v_pk_mul_f32 v[146:147], v[146:147], v[148:149]
	v_pk_mul_f32 v[86:87], v[86:87], v[134:135]
	v_pk_mul_f32 v[88:89], v[88:89], v[146:147]
	v_cvt_f32_ubyte3_e32 v135, v137
	v_cvt_f32_ubyte2_e32 v134, v137
	v_cvt_f32_ubyte1_e32 v147, v137
	v_cvt_f32_ubyte0_e32 v146, v137
	v_pk_mul_f32 v[90:91], v[90:91], v[146:147]
	v_pk_mul_f32 v[92:93], v[92:93], v[134:135]
	v_pk_mul_f32 v[78:79], v[78:79], v[90:91]
	v_pk_mul_f32 v[80:81], v[80:81], v[92:93]
	v_mov_b32_e32 v90, v162
	s_add_u32 s6, s35, 0x13808000
	v_ashrrev_i32_e32 v91, 31, v90
	v_lshl_add_u64 v[90:91], v[90:91], 4, s[12:13]
	global_load_dwordx4 v[134:137], v[90:91], off
	v_mov_b32_e32 v90, v162
	s_addc_u32 s7, vcc_lo, 0
	v_ashrrev_i32_e32 v91, 31, v90
	v_lshl_add_u64 v[90:91], v[90:91], 4, s[6:7]
	global_load_dwordx4 v[146:149], v[90:91], off
	s_waitcnt vmcnt(1)
	v_cvt_f32_ubyte3_e32 v173, v134
	v_cvt_f32_ubyte2_e32 v172, v134
	v_cvt_f32_ubyte1_e32 v193, v134
	v_cvt_f32_ubyte0_e32 v192, v134
	s_waitcnt vmcnt(0)
	v_cvt_f32_ubyte0_e32 v91, v148
	v_cvt_f32_ubyte1_e32 v92, v148
	v_cvt_f32_ubyte2_e32 v93, v148
	v_cvt_f32_ubyte0_e32 v90, v146
	v_rcp_iflag_f32_e32 v150, v91
	v_cvt_f32_ubyte1_e32 v91, v146
	v_rcp_iflag_f32_e32 v151, v92
	v_cvt_f32_ubyte2_e32 v92, v146
	v_rcp_iflag_f32_e32 v152, v93
	v_cvt_f32_ubyte3_e32 v93, v146
	v_rcp_iflag_f32_e32 v90, v90
	v_rcp_iflag_f32_e32 v91, v91
	v_rcp_iflag_f32_e32 v92, v92
	v_rcp_iflag_f32_e32 v93, v93
	v_cvt_f32_ubyte3_e32 v146, v148
	v_rcp_iflag_f32_e32 v153, v146
	v_pk_mul_f32 v[90:91], v[90:91], v[192:193]
	v_pk_mul_f32 v[92:93], v[92:93], v[172:173]
	v_pk_mul_f32 v[90:91], v[106:107], v[90:91]
	v_pk_mul_f32 v[92:93], v[108:109], v[92:93]
	v_cvt_f32_ubyte3_e32 v107, v136
	v_cvt_f32_ubyte2_e32 v106, v136
	v_cvt_f32_ubyte1_e32 v109, v136
	v_cvt_f32_ubyte0_e32 v108, v136
	v_pk_mul_f32 v[108:109], v[150:151], v[108:109]
	v_pk_mul_f32 v[106:107], v[152:153], v[106:107]
	v_pk_mul_f32 v[98:99], v[98:99], v[108:109]
	v_pk_mul_f32 v[100:101], v[100:101], v[106:107]
	v_cvt_f32_ubyte0_e32 v106, v147
	v_cvt_f32_ubyte1_e32 v107, v147
	v_cvt_f32_ubyte2_e32 v108, v147
	v_cvt_f32_ubyte3_e32 v109, v147
	v_rcp_iflag_f32_e32 v150, v106
	v_rcp_iflag_f32_e32 v151, v107
	v_rcp_iflag_f32_e32 v146, v108
	v_rcp_iflag_f32_e32 v147, v109
	v_cvt_f32_ubyte0_e32 v106, v149
	v_cvt_f32_ubyte1_e32 v107, v149
	v_cvt_f32_ubyte2_e32 v108, v149
	v_cvt_f32_ubyte3_e32 v109, v149
	v_rcp_iflag_f32_e32 v106, v106
	v_rcp_iflag_f32_e32 v107, v107
	v_rcp_iflag_f32_e32 v108, v108
	v_rcp_iflag_f32_e32 v109, v109
	v_cvt_f32_ubyte3_e32 v149, v135
	v_cvt_f32_ubyte2_e32 v148, v135
	v_cvt_f32_ubyte1_e32 v153, v135
	v_cvt_f32_ubyte0_e32 v152, v135
	v_pk_mul_f32 v[134:135], v[150:151], v[152:153]
	v_pk_mul_f32 v[146:147], v[146:147], v[148:149]
	v_pk_mul_f32 v[102:103], v[102:103], v[134:135]
	v_pk_mul_f32 v[104:105], v[104:105], v[146:147]
	v_cvt_f32_ubyte3_e32 v135, v137
	v_cvt_f32_ubyte2_e32 v134, v137
	v_cvt_f32_ubyte1_e32 v147, v137
	v_cvt_f32_ubyte0_e32 v146, v137
	v_pk_mul_f32 v[106:107], v[106:107], v[146:147]
	v_pk_mul_f32 v[108:109], v[108:109], v[134:135]
	v_pk_mul_f32 v[94:95], v[94:95], v[106:107]
	v_pk_mul_f32 v[96:97], v[96:97], v[108:109]
	v_mov_b32_e32 v106, v162
	s_add_u32 s10, s35, 0x1380a000
	v_ashrrev_i32_e32 v107, 31, v106
	v_lshl_add_u64 v[106:107], v[106:107], 4, s[16:17]
	global_load_dwordx4 v[134:137], v[106:107], off
	v_mov_b32_e32 v106, v162
	s_addc_u32 s11, vcc_lo, 0
	v_ashrrev_i32_e32 v107, 31, v106
	v_lshl_add_u64 v[106:107], v[106:107], 4, s[10:11]
	global_load_dwordx4 v[146:149], v[106:107], off
	s_waitcnt vmcnt(1)
	v_cvt_f32_ubyte3_e32 v173, v134
	v_cvt_f32_ubyte2_e32 v172, v134
	v_cvt_f32_ubyte1_e32 v193, v134
	v_cvt_f32_ubyte0_e32 v192, v134
	s_waitcnt vmcnt(0)
; DI float frcp(float x) { return __builtin_amdgcn_rcpf(x); }
; DI u32x4* gate_slot(const Params& P, int tile, int j, int g8) { return (u32x4*)slotp(P, SL_SK) + ((size_t)(tile * 3 + j) * 8 + g8) * 512 + tid(); }
; DI void merge_scale(const Params& P, int tile, int seg, f32x4 (&acc)[2][2][4][2]) {
; #pragma unroll
;     for (int g8 = 0; g8 < 8; ++g8) {
;         const int ai = g8 >> 2, bj = (g8 >> 1) & 1, nn = g8 & 1;
;         const u32x4 ga = *gate_slot(P, tile, seg, g8), gb = *gate_slot(P, tile, seg + 1, g8);
; #pragma unroll
;         for (int e = 0; e < 8; ++e) {
;             const float rl = (float)((ga[e >> 2] >> (8 * (e & 3))) & 255u) * frcp((float)((gb[e >> 2] >> (8 * (e & 3))) & 255u));
;             const float rh = (float)((ga[2 + (e >> 2)] >> (8 * (e & 3))) & 255u) * frcp((float)((gb[2 + (e >> 2)] >> (8 * (e & 3))) & 255u));
;             acc[ai][bj][e >> 2][nn][e & 3] *= rl;
;             acc[ai][bj][2 + (e >> 2)][nn][e & 3] *= rh;
;         }
;         __builtin_amdgcn_sched_barrier(0);
;     }
; }
	v_cvt_f32_ubyte0_e32 v107, v148
	v_cvt_f32_ubyte1_e32 v108, v148
	v_cvt_f32_ubyte2_e32 v109, v148
	v_cvt_f32_ubyte0_e32 v106, v146
	v_rcp_iflag_f32_e32 v150, v107
	v_cvt_f32_ubyte1_e32 v107, v146
	v_rcp_iflag_f32_e32 v151, v108
	v_cvt_f32_ubyte2_e32 v108, v146
	v_rcp_iflag_f32_e32 v152, v109
	v_cvt_f32_ubyte3_e32 v109, v146
	v_rcp_iflag_f32_e32 v106, v106
	v_rcp_iflag_f32_e32 v107, v107
	v_rcp_iflag_f32_e32 v108, v108
	v_rcp_iflag_f32_e32 v109, v109
	v_cvt_f32_ubyte3_e32 v146, v148
	v_rcp_iflag_f32_e32 v153, v146
	v_pk_mul_f32 v[106:107], v[106:107], v[192:193]
	v_pk_mul_f32 v[108:109], v[108:109], v[172:173]
	v_pk_mul_f32 v[106:107], v[122:123], v[106:107]
	v_pk_mul_f32 v[108:109], v[124:125], v[108:109]
	v_cvt_f32_ubyte3_e32 v123, v136
	v_cvt_f32_ubyte2_e32 v122, v136
	v_cvt_f32_ubyte1_e32 v125, v136
	v_cvt_f32_ubyte0_e32 v124, v136
	v_pk_mul_f32 v[124:125], v[150:151], v[124:125]
	v_pk_mul_f32 v[122:123], v[152:153], v[122:123]
	v_pk_mul_f32 v[114:115], v[114:115], v[124:125]
	v_pk_mul_f32 v[116:117], v[116:117], v[122:123]
	v_cvt_f32_ubyte0_e32 v122, v147
	v_cvt_f32_ubyte1_e32 v123, v147
	v_cvt_f32_ubyte2_e32 v124, v147
	v_cvt_f32_ubyte3_e32 v125, v147
	v_rcp_iflag_f32_e32 v150, v122
	v_rcp_iflag_f32_e32 v151, v123
	v_rcp_iflag_f32_e32 v146, v124
	v_rcp_iflag_f32_e32 v147, v125
	v_cvt_f32_ubyte0_e32 v122, v149
	v_cvt_f32_ubyte1_e32 v123, v149
	v_cvt_f32_ubyte2_e32 v124, v149
	v_cvt_f32_ubyte3_e32 v125, v149
	v_rcp_iflag_f32_e32 v122, v122
	v_rcp_iflag_f32_e32 v123, v123
	v_rcp_iflag_f32_e32 v124, v124
	v_rcp_iflag_f32_e32 v125, v125
	v_cvt_f32_ubyte3_e32 v149, v135
	v_cvt_f32_ubyte2_e32 v148, v135
	v_cvt_f32_ubyte1_e32 v153, v135
	v_cvt_f32_ubyte0_e32 v152, v135
	v_pk_mul_f32 v[134:135], v[150:151], v[152:153]
	v_pk_mul_f32 v[146:147], v[146:147], v[148:149]
	v_pk_mul_f32 v[118:119], v[118:119], v[134:135]
	v_pk_mul_f32 v[120:121], v[120:121], v[146:147]
	v_cvt_f32_ubyte3_e32 v135, v137
	v_cvt_f32_ubyte2_e32 v134, v137
	v_cvt_f32_ubyte1_e32 v147, v137
	v_cvt_f32_ubyte0_e32 v146, v137
	v_pk_mul_f32 v[122:123], v[122:123], v[146:147]
	v_pk_mul_f32 v[124:125], v[124:125], v[134:135]
	v_pk_mul_f32 v[110:111], v[110:111], v[122:123]
	v_pk_mul_f32 v[112:113], v[112:113], v[124:125]
	v_mov_b32_e32 v122, v162
	s_add_u32 s12, s35, 0x1380c000
	v_ashrrev_i32_e32 v123, 31, v122
	v_lshl_add_u64 v[122:123], v[122:123], 4, s[20:21]
	global_load_dwordx4 v[134:137], v[122:123], off
	v_mov_b32_e32 v122, v162
	s_addc_u32 s13, vcc_lo, 0
	v_ashrrev_i32_e32 v123, 31, v122
	v_lshl_add_u64 v[122:123], v[122:123], 4, s[12:13]
	global_load_dwordx4 v[146:149], v[122:123], off
	s_waitcnt vmcnt(1)
	v_cvt_f32_ubyte3_e32 v173, v134
	v_cvt_f32_ubyte2_e32 v172, v134
	v_cvt_f32_ubyte1_e32 v193, v134
	v_cvt_f32_ubyte0_e32 v192, v134
	s_waitcnt vmcnt(0)
; DI float frcp(float x) { return __builtin_amdgcn_rcpf(x); }
; DI u32x4* gate_slot(const Params& P, int tile, int j, int g8) { return (u32x4*)slotp(P, SL_SK) + ((size_t)(tile * 3 + j) * 8 + g8) * 512 + tid(); }
; DI void merge_scale(const Params& P, int tile, int seg, f32x4 (&acc)[2][2][4][2]) {
; #pragma unroll
;     for (int g8 = 0; g8 < 8; ++g8) {
;         const int ai = g8 >> 2, bj = (g8 >> 1) & 1, nn = g8 & 1;
;         const u32x4 ga = *gate_slot(P, tile, seg, g8), gb = *gate_slot(P, tile, seg + 1, g8);
; #pragma unroll
;         for (int e = 0; e < 8; ++e) {
;             const float rl = (float)((ga[e >> 2] >> (8 * (e & 3))) & 255u) * frcp((float)((gb[e >> 2] >> (8 * (e & 3))) & 255u));
;             const float rh = (float)((ga[2 + (e >> 2)] >> (8 * (e & 3))) & 255u) * frcp((float)((gb[2 + (e >> 2)] >> (8 * (e & 3))) & 255u));
;             acc[ai][bj][e >> 2][nn][e & 3] *= rl;
;             acc[ai][bj][2 + (e >> 2)][nn][e & 3] *= rh;
;         }
;         __builtin_amdgcn_sched_barrier(0);
;     }
; }
	v_cvt_f32_ubyte0_e32 v123, v148
	v_cvt_f32_ubyte1_e32 v124, v148
	v_cvt_f32_ubyte2_e32 v125, v148
	v_cvt_f32_ubyte0_e32 v122, v146
	v_rcp_iflag_f32_e32 v150, v123
	v_cvt_f32_ubyte1_e32 v123, v146
	v_rcp_iflag_f32_e32 v151, v124
	v_cvt_f32_ubyte2_e32 v124, v146
	v_rcp_iflag_f32_e32 v152, v125
	v_cvt_f32_ubyte3_e32 v125, v146
	v_rcp_iflag_f32_e32 v122, v122
	v_rcp_iflag_f32_e32 v123, v123
	v_rcp_iflag_f32_e32 v124, v124
	v_rcp_iflag_f32_e32 v125, v125
	v_cvt_f32_ubyte3_e32 v146, v148
	v_rcp_iflag_f32_e32 v153, v146
	v_pk_mul_f32 v[122:123], v[122:123], v[192:193]
	v_pk_mul_f32 v[124:125], v[124:125], v[172:173]
	v_pk_mul_f32 v[122:123], v[126:127], v[122:123]
	v_pk_mul_f32 v[124:125], v[128:129], v[124:125]
	v_cvt_f32_ubyte3_e32 v127, v136
	v_cvt_f32_ubyte2_e32 v126, v136
	v_cvt_f32_ubyte1_e32 v129, v136
	v_cvt_f32_ubyte0_e32 v128, v136
	v_pk_mul_f32 v[128:129], v[150:151], v[128:129]
	v_pk_mul_f32 v[126:127], v[152:153], v[126:127]
	v_pk_mul_f32 v[38:39], v[38:39], v[128:129]
	v_pk_mul_f32 v[40:41], v[40:41], v[126:127]
	v_cvt_f32_ubyte0_e32 v126, v147
	v_cvt_f32_ubyte1_e32 v127, v147
	v_cvt_f32_ubyte2_e32 v128, v147
	v_cvt_f32_ubyte3_e32 v129, v147
	v_rcp_iflag_f32_e32 v150, v126
	v_rcp_iflag_f32_e32 v151, v127
	v_rcp_iflag_f32_e32 v146, v128
	v_rcp_iflag_f32_e32 v147, v129
	v_cvt_f32_ubyte0_e32 v126, v149
	v_cvt_f32_ubyte1_e32 v127, v149
	v_cvt_f32_ubyte2_e32 v128, v149
	v_cvt_f32_ubyte3_e32 v129, v149
	v_rcp_iflag_f32_e32 v126, v126
	v_rcp_iflag_f32_e32 v127, v127
	v_rcp_iflag_f32_e32 v128, v128
	v_rcp_iflag_f32_e32 v129, v129
	v_cvt_f32_ubyte3_e32 v149, v135
	v_cvt_f32_ubyte2_e32 v148, v135
	v_cvt_f32_ubyte1_e32 v153, v135
	v_cvt_f32_ubyte0_e32 v152, v135
	v_pk_mul_f32 v[134:135], v[150:151], v[152:153]
	v_pk_mul_f32 v[146:147], v[146:147], v[148:149]
	v_pk_mul_f32 v[34:35], v[34:35], v[134:135]
	v_pk_mul_f32 v[36:37], v[36:37], v[146:147]
	v_cvt_f32_ubyte3_e32 v135, v137
	v_cvt_f32_ubyte2_e32 v134, v137
	v_cvt_f32_ubyte1_e32 v147, v137
	v_cvt_f32_ubyte0_e32 v146, v137
	v_pk_mul_f32 v[126:127], v[126:127], v[146:147]
	v_pk_mul_f32 v[128:129], v[128:129], v[134:135]
	v_pk_mul_f32 v[22:23], v[22:23], v[126:127]
	v_pk_mul_f32 v[24:25], v[24:25], v[128:129]
	v_mov_b32_e32 v126, v162
	s_add_u32 s16, s35, 0x1380e000
	v_ashrrev_i32_e32 v127, 31, v126
	v_lshl_add_u64 v[126:127], v[126:127], 4, s[22:23]
	v_mov_b32_e32 v134, v162
	global_load_dwordx4 v[126:129], v[126:127], off
	s_addc_u32 s17, vcc_lo, 0
	v_ashrrev_i32_e32 v135, 31, v134
	v_lshl_add_u64 v[134:135], v[134:135], 4, s[16:17]
	global_load_dwordx4 v[146:149], v[134:135], off
	s_waitcnt vmcnt(1)
	v_cvt_f32_ubyte3_e32 v173, v126
	v_cvt_f32_ubyte2_e32 v172, v126
	v_cvt_f32_ubyte1_e32 v193, v126
	v_cvt_f32_ubyte0_e32 v192, v126
	s_waitcnt vmcnt(0)
	v_cvt_f32_ubyte0_e32 v135, v148
	v_cvt_f32_ubyte0_e32 v134, v146
	v_rcp_iflag_f32_e32 v136, v135
	v_cvt_f32_ubyte1_e32 v135, v146
	v_cvt_f32_ubyte2_e32 v150, v146
	v_cvt_f32_ubyte2_e32 v151, v148
	v_cvt_f32_ubyte3_e32 v146, v146
	v_rcp_iflag_f32_e32 v134, v134
	v_rcp_iflag_f32_e32 v135, v135
	v_rcp_iflag_f32_e32 v150, v150
	v_rcp_iflag_f32_e32 v152, v151
	v_rcp_iflag_f32_e32 v151, v146
	v_cvt_f32_ubyte1_e32 v137, v148
	v_cvt_f32_ubyte3_e32 v146, v148
	v_rcp_iflag_f32_e32 v137, v137
	v_rcp_iflag_f32_e32 v153, v146
	v_pk_mul_f32 v[134:135], v[134:135], v[192:193]
	v_pk_mul_f32 v[150:151], v[150:151], v[172:173]
	v_pk_mul_f32 v[14:15], v[14:15], v[134:135]
	v_pk_mul_f32 v[16:17], v[16:17], v[150:151]
	v_cvt_f32_ubyte3_e32 v135, v128
	v_cvt_f32_ubyte2_e32 v134, v128
	v_cvt_f32_ubyte1_e32 v151, v128
	v_cvt_f32_ubyte0_e32 v150, v128
	v_cvt_f32_ubyte0_e32 v126, v147
	v_pk_mul_f32 v[136:137], v[136:137], v[150:151]
	v_pk_mul_f32 v[134:135], v[152:153], v[134:135]
	v_rcp_iflag_f32_e32 v150, v126
	v_cvt_f32_ubyte0_e32 v126, v149
	v_pk_mul_f32 v[12:13], v[12:13], v[134:135]
	v_rcp_iflag_f32_e32 v134, v126
	v_cvt_f32_ubyte1_e32 v126, v147
	v_rcp_iflag_f32_e32 v151, v126
	v_cvt_f32_ubyte1_e32 v126, v149
	v_rcp_iflag_f32_e32 v135, v126
	v_cvt_f32_ubyte2_e32 v126, v147
	v_rcp_iflag_f32_e32 v146, v126
	v_cvt_f32_ubyte2_e32 v126, v149
	v_pk_mul_f32 v[10:11], v[10:11], v[136:137]
	v_rcp_iflag_f32_e32 v136, v126
	v_cvt_f32_ubyte3_e32 v126, v147
	v_rcp_iflag_f32_e32 v147, v126
	v_cvt_f32_ubyte3_e32 v126, v149
	v_rcp_iflag_f32_e32 v137, v126
	v_cvt_f32_ubyte3_e32 v149, v127
	v_cvt_f32_ubyte2_e32 v148, v127
	v_cvt_f32_ubyte1_e32 v153, v127
	v_cvt_f32_ubyte0_e32 v152, v127
	v_pk_mul_f32 v[126:127], v[150:151], v[152:153]
	v_pk_mul_f32 v[146:147], v[146:147], v[148:149]
	v_pk_mul_f32 v[6:7], v[6:7], v[126:127]
	v_pk_mul_f32 v[8:9], v[8:9], v[146:147]
	v_cvt_f32_ubyte3_e32 v127, v129
	v_cvt_f32_ubyte2_e32 v126, v129
	v_cvt_f32_ubyte1_e32 v147, v129
	v_cvt_f32_ubyte0_e32 v146, v129
	v_pk_mul_f32 v[128:129], v[134:135], v[146:147]
	v_pk_mul_f32 v[126:127], v[136:137], v[126:127]
	v_pk_mul_f32 v[2:3], v[2:3], v[128:129]
	v_pk_mul_f32 v[4:5], v[4:5], v[126:127]
	s_mov_b32 s23, 14
	s_mov_b64 s[20:21], 0
	s_mov_b64 s[36:37], 0x20080
	s_mov_b64 s[42:43], 0x20100
	s_mov_b64 s[44:45], 0x20180
